# P5 A2 Neumann steps hand-scheduled: all LDS reads up front, counted lgkmcnt, per-wave-class straight-line code
# speedup vs baseline: 1.1142x; 1.1142x over previous
; #define GAS __attribute__((address_space(1)))
; #define LAS __attribute__((address_space(3)))
; __device__ __forceinline__ void rwkv_chunk_group(Frame& F, int bc, unsigned long long& tsub) {
;     ...
;         for (int tt = 0; tt < 8; ++tt) { const float kn = kkv[tt] * __builtin_amdgcn_rsqf(fmaxf(sq[tt], 1e-24f));
;             aa[tt] = -kn; bb[tt] = kn * icv[tt]; vbv[tt] = bq[tt] * vv[tt]; }
;         *(LAS float*)(L + L_GT + (w * 64 + ch) * 4) = run;
;         *(GAS v4u*)(VBp + ch * 64 + tb) = (v4u){pk2(vbv[0], vbv[1]), pk2(vbv[2], vbv[3]), pk2(vbv[4], vbv[5]), pk2(vbv[6], vbv[7])};
;         *(GAS v4u*)(Gp + ch * 64 + tb) = (v4u){pk2(ggv[0], ggv[1]), pk2(ggv[2], ggv[3]), pk2(ggv[4], ggv[5]), pk2(ggv[6], ggv[7])};
;         if (hh + 1 < RW_H) {
;             const bool has = (c * CH + tb > 0);
; #pragma unroll
;             for (int tt = 0; tt < 9; ++tt) { const size_t off = (size_t)(row0 + tb + tt - 1) * PRW + hnext * 64 + ch;
;                 if (tt > 0 || has) { raw[tt][0] = P[off]; raw[tt][1] = P[off + 512]; raw[tt][2] = P[off + 1024]; } }
;         }
;         LBAR();
;         float offs = 0.f, tot = 0.f;
; #pragma unroll
;         for (int g = 0; g < 8; ++g) { const float x = *(const LAS float*)(L + L_GT + (g * 64 + ch) * 4); if (g < w) offs += x; tot += x; }
;         const float etot = __expf(tot);
;         if (w == 0) *(LAS float*)(L + L_WC + ch * 4) = etot;
;         unsigned patt[4], pvt[4], pbh[4], pkh[4]; float hAt = 0.f, hBh = 0.f, hKh = 0.f;
;         float e_ex = __expf(offs);
; #pragma unroll
;         for (int tt = 0; tt < 8; ++tt) { const int t = tb + tt; const float cl = offs + ld[tt];
;             const float e_in = __expf(cl), e_inv = __builtin_amdgcn_rcpf(e_in), e_hat = etot * e_inv;
;             const float At = aa[tt] * e_ex, Bt = bb[tt] * e_inv, Kt = kp[tt] * e_inv, Rt = rr[tt] * e_in, Bh = bb[tt] * e_hat, Kh = kp[tt] * e_hat; e_ex = e_in;
;             *(LAS bf16*)(L + L_AT + t * LD + ch * 2) = (bf16)f2bf(At); *(LAS bf16*)(L + L_BT + t * LD + ch * 2) = (bf16)f2bf(Bt);
;             *(LAS bf16*)(L + L_KT + t * LD + ch * 2) = (bf16)f2bf(Kt); *(LAS bf16*)(L + L_RT + t * LD + ch * 2) = (bf16)f2bf(Rt);
;             if (tt & 1) { patt[tt >> 1] = pk2(hAt, At); pvt[tt >> 1] = pk2(vv[tt - 1], vv[tt]); pbh[tt >> 1] = pk2(hBh, Bh); pkh[tt >> 1] = pk2(hKh, Kh); }
;             hAt = At; hBh = Bh; hKh = Kh;
;         }
.LBB0_1418:
	v_cndmask_b32_e64 v182, v185, 0, s[82:83]
	v_readlane_b32 s66, v254, 40
	v_add_f32_e32 v47, v47, v182
	v_readlane_b32 s67, v254, 41
	s_or_b64 vcc, s[40:41], s[50:51]
	s_mov_b32 s17, s16
	v_cndmask_b32_e64 v47, v182, v47, s[66:67]
	v_readlane_b32 s66, v254, 42
	v_add_f32_e32 v102, v102, v47
	v_readlane_b32 s67, v254, 43
	s_nop 1
	v_cndmask_b32_e64 v47, v47, v102, s[66:67]
	v_readlane_b32 s66, v254, 44
	v_add_f32_e32 v102, v103, v47
	v_readlane_b32 s67, v254, 45
	s_nop 1
	v_cndmask_b32_e64 v47, v47, v102, s[66:67]
	v_readlane_b32 s66, v254, 46
	v_add_f32_e32 v98, v98, v47
	v_readlane_b32 s67, v254, 47
	s_nop 1
	v_cndmask_b32_e64 v47, v47, v98, s[66:67]
	v_readlane_b32 s66, v254, 48
	v_add_f32_e32 v98, v99, v47
	v_readlane_b32 s67, v254, 49
	v_max_f32_e64 v99, s77, s77
	v_max_f32_e32 v99, 0x179abe15, v99
	v_cndmask_b32_e64 v47, v47, v98, s[66:67]
	v_readlane_b32 s66, v254, 50
	v_max_f32_e64 v98, s71, s71
	v_add_f32_e32 v96, v96, v47
	v_readlane_b32 s67, v254, 51
	v_max_f32_e32 v98, 0x179abe15, v98
	v_rsq_f32_e32 v98, v98
	v_cndmask_b32_e64 v47, v47, v96, s[66:67]
	v_rsq_f32_e32 v99, v99
	v_add_f32_e32 v102, v97, v47
	v_max_f32_e64 v97, s14, s14
	v_readlane_b32 s14, v254, 53
	v_readlane_b32 s15, v254, 54
	v_pk_mul_f32 v[88:89], v[88:89], v[98:99]
	v_max_f32_e64 v98, s69, s69
	v_cndmask_b32_e64 v47, v47, v102, s[14:15]
	v_max_f32_e64 v99, s70, s70
	v_add_f32_e32 v102, v177, v47
	v_max_f32_e32 v98, 0x179abe15, v98
	v_max_f32_e32 v99, 0x179abe15, v99
	v_mul_f32_e32 v102, 0x3fb8aa3b, v102
	v_max_f32_e64 v96, s93, s93
	v_rsq_f32_e32 v98, v98
	v_rsq_f32_e32 v99, v99
	v_exp_f32_e32 v103, v102
	v_max_f32_e32 v96, 0x179abe15, v96
	v_max_f32_e32 v97, 0x179abe15, v97
	v_rsq_f32_e32 v96, v96
	v_rsq_f32_e32 v97, v97
	v_pk_mul_f32 v[98:99], v[80:81], v[98:99]
	v_rcp_f32_e32 v80, v103
	v_mul_f32_e32 v81, 0x3fb8aa3b, v47
	v_pk_mul_f32 v[96:97], v[100:101], v[96:97]
	v_exp_f32_e32 v102, v81
	v_pk_mul_f32 v[38:39], v[38:39], v[96:97]
	s_mul_i32 s14, s16, 0x480
	v_mul_f32_e32 v81, v38, v80
	v_pk_mul_f32 v[186:187], v[86:87], v[98:99]
	v_mul_f32_e32 v86, v40, v80
	v_mul_f32_e32 v87, v173, v103
	v_cvt_pk_bf16_f32 v81, v81, s0
	v_add_u32_e32 v173, s14, v58
	ds_write_b16 v173, v81 offset:9216
	v_cvt_pk_bf16_f32 v81, v86, s0
	v_add_f32_e32 v86, v176, v47
	v_mul_f32_e32 v86, 0x3fb8aa3b, v86
	v_max_f32_e64 v100, s64, s64
	v_max_f32_e64 v101, s65, s65
	v_exp_f32_e32 v176, v86
	v_max_f32_e32 v100, 0x179abe15, v100
	v_max_f32_e32 v101, 0x179abe15, v101
	v_rsq_f32_e32 v100, v100
	v_rsq_f32_e32 v101, v101
	ds_write_b16 v173, v81 offset:18432
	v_cvt_pk_bf16_f32 v81, v87, s0
	ds_write_b16 v173, v81 offset:27648
	v_rcp_f32_e32 v81, v176
	v_pk_mul_f32 v[44:45], v[44:45], v[100:101]
	v_pk_mul_f32 v[86:87], v[102:103], v[96:97] neg_lo:[0,1] neg_hi:[0,1]
	v_pk_mul_f32 v[100:101], v[94:95], v[44:45]
	v_cvt_pk_bf16_f32 v94, v86, s0
	ds_write_b16 v173, v94
	v_mul_f32_e32 v94, v39, v81
	v_mul_f32_e32 v95, v41, v81
	v_cvt_pk_bf16_f32 v94, v94, s0
	v_mul_f32_e32 v96, v174, v176
	ds_write_b16 v173, v94 offset:9360
	v_cvt_pk_bf16_f32 v94, v95, s0
	ds_write_b16 v173, v94 offset:18576
	v_cvt_pk_bf16_f32 v94, v96, s0
	ds_write_b16 v173, v94 offset:27792
	v_add_f32_e32 v94, v179, v47
	v_mul_f32_e32 v94, 0x3fb8aa3b, v94
	v_exp_f32_e32 v177, v94
	v_pk_mul_f32 v[82:83], v[82:83], v[88:89]
	v_pk_mul_f32 v[80:81], v[46:47], v[80:81] op_sel_hi:[0,1]
	v_pk_mul_f32 v[40:41], v[40:41], v[80:81]
	v_rcp_f32_e32 v96, v177
	v_pk_mul_f32 v[94:95], v[38:39], v[80:81]
	v_cvt_pk_bf16_f32 v80, v36, v37
	v_cvt_pk_bf16_f32 v97, v87, s0
	v_mul_f32_e32 v36, v82, v96
	v_cvt_pk_bf16_f32 v36, v36, s0
	ds_write_b16 v173, v36 offset:9504
	v_add_f32_e32 v36, v181, v47
	v_mul_f32_e32 v36, 0x3fb8aa3b, v36
	v_exp_f32_e32 v36, v36
	ds_write_b16 v173, v97 offset:144
	v_mul_f32_e32 v37, v78, v96
	v_mul_f32_e32 v39, v175, v177
	v_rcp_f32_e32 v97, v36
	v_cvt_pk_bf16_f32 v37, v37, s0
	v_cvt_pk_bf16_f32 v38, v86, v87
	v_cvt_pk_bf16_f32 v86, v94, v95
	v_cvt_pk_bf16_f32 v94, v40, v41
	ds_write_b16 v173, v37 offset:18720
	v_cvt_pk_bf16_f32 v37, v39, s0
	v_pk_mul_f32 v[40:41], v[176:177], v[88:89] neg_lo:[0,1] neg_hi:[0,1]
	ds_write_b16 v173, v37 offset:27936
	v_cvt_pk_bf16_f32 v37, v40, s0
	ds_write_b16 v173, v37 offset:288
	v_mul_f32_e32 v37, v83, v97
	v_mul_f32_e32 v39, v79, v97
	v_cvt_pk_bf16_f32 v37, v37, s0
	v_mul_f32_e32 v81, v178, v36
	ds_write_b16 v173, v37 offset:9648
	v_cvt_pk_bf16_f32 v37, v39, s0
	ds_write_b16 v173, v37 offset:18864
	v_cvt_pk_bf16_f32 v37, v81, s0
	ds_write_b16 v173, v37 offset:28080
	v_add_f32_e32 v37, v184, v47
	v_mul_f32_e32 v37, 0x3fb8aa3b, v37
	v_exp_f32_e32 v37, v37
	v_cvt_pk_bf16_f32 v39, v40, v41
	v_cvt_pk_bf16_f32 v87, v41, s0
	v_cvt_pk_bf16_f32 v81, v76, v77
	v_rcp_f32_e32 v40, v37
	v_mul_f32_e32 v77, v180, v37
	v_pk_mul_f32 v[36:37], v[36:37], v[98:99] neg_lo:[0,1] neg_hi:[0,1]
	v_pk_mul_f32 v[88:89], v[46:47], v[96:97] op_sel_hi:[0,1]
	v_mul_f32_e32 v41, v186, v40
	v_mul_f32_e32 v76, v90, v40
	v_cvt_pk_bf16_f32 v41, v41, s0
	ds_write_b16 v173, v41 offset:9792
	v_cvt_pk_bf16_f32 v41, v76, s0
	v_add_f32_e32 v76, v190, v47
	v_mul_f32_e32 v76, 0x3fb8aa3b, v76
	v_exp_f32_e32 v76, v76
	ds_write_b16 v173, v41 offset:19008
	v_cvt_pk_bf16_f32 v41, v77, s0
	ds_write_b16 v173, v41 offset:28224
	v_rcp_f32_e32 v41, v76
	v_cvt_pk_bf16_f32 v77, v36, s0
	v_pk_mul_f32 v[78:79], v[78:79], v[88:89]
	ds_write_b16 v173, v77 offset:576
	v_mul_f32_e32 v77, v187, v41
	v_cvt_pk_bf16_f32 v95, v78, v79
	v_mul_f32_e32 v78, v91, v41
	v_cvt_pk_bf16_f32 v77, v77, s0
	v_mul_f32_e32 v79, v183, v76
	ds_write_b16 v173, v77 offset:9936
	v_cvt_pk_bf16_f32 v77, v78, s0
	ds_write_b16 v173, v77 offset:19152
; __device__ __forceinline__ void rwkv_chunk_group(Frame& F, int bc, unsigned long long& tsub) {
;     ...
;         for (int tt = 0; tt < 8; ++tt) { const int t = tb + tt; const float cl = offs + ld[tt];
;             const float e_in = __expf(cl), e_inv = __builtin_amdgcn_rcpf(e_in), e_hat = etot * e_inv;
;             const float At = aa[tt] * e_ex, Bt = bb[tt] * e_inv, Kt = kp[tt] * e_inv, Rt = rr[tt] * e_in, Bh = bb[tt] * e_hat, Kh = kp[tt] * e_hat; e_ex = e_in;
;             *(LAS bf16*)(L + L_AT + t * LD + ch * 2) = (bf16)f2bf(At); *(LAS bf16*)(L + L_BT + t * LD + ch * 2) = (bf16)f2bf(Bt);
;             *(LAS bf16*)(L + L_KT + t * LD + ch * 2) = (bf16)f2bf(Kt); *(LAS bf16*)(L + L_RT + t * LD + ch * 2) = (bf16)f2bf(Rt);
;             if (tt & 1) { patt[tt >> 1] = pk2(hAt, At); pvt[tt >> 1] = pk2(vv[tt - 1], vv[tt]); pbh[tt >> 1] = pk2(hBh, Bh); pkh[tt >> 1] = pk2(hKh, Kh); }
;             hAt = At; hBh = Bh; hKh = Kh;
;         }
;         *(LAS v4u*)(L + L_ATT + ch * LD + tb * 2) = (v4u){patt[0], patt[1], patt[2], patt[3]};
;         *(LAS v4u*)(L + L_VT + ch * LD + tb * 2) = (v4u){pvt[0], pvt[1], pvt[2], pvt[3]};
;         *(LAS v4u*)(L + L_BH + ch * LD + tb * 2) = (v4u){pbh[0], pbh[1], pbh[2], pbh[3]};
;         *(LAS v4u*)(L + L_KH + ch * LD + tb * 2) = (v4u){pkh[0], pkh[1], pkh[2], pkh[3]};
;         LBAR();
;     }
;     TSUB(2);
; #pragma unroll
;     for (int q = 0; q < 2; ++q) { const int tw = 2 * w + q, p0 = 16 * (tw >> 2), q0 = 16 * (tw & 3);
;         f32x4 m = mm_tile(L + L_AT, LD, q0, L + L_BT, LD, p0, 2, Z4, fr, fq);
;         f32x4 nak = mm_tile(L + L_KT, LD, q0, L + L_AT, LD, p0, 2, Z4, fr, fq);
;         f32x4 nrk = mm_tile(L + L_KT, LD, q0, L + L_RT, LD, p0, 2, Z4, fr, fq);
;         f32x4 nrb = mm_tile(L + L_BT, LD, q0, L + L_RT, LD, p0, 2, Z4, fr, fq);
;         f32x4 tt;
;         const int p = p0 + fr;
; #pragma unroll
;         for (int v = 0; v < 4; ++v) { const int qq = q0 + 4 * fq + v;
;             if (!(p < qq)) m[v] = 0.f;
;             if (!(qq < p)) nak[v] = 0.f;
;             if (!(qq <= p)) { nrk[v] = 0.f; nrb[v] = 0.f; }
;             tt[v] = (p == qq) ? 1.f : 0.f; }
;         const int o = p * LD + (q0 + 4 * fq) * 2;
;         st4_lds(L + L_M + o, m); st4t_lds(L + L_MT, p, q0 + 4 * fq, m); st4_lds(L + L_NAK + o, nak); st4_lds(L + L_NRK + o, nrk); st4_lds(L + L_NRB + o, nrb); st4_lds(L + L_TT + o, tt);
	v_cvt_pk_bf16_f32 v77, v79, s0
	ds_write_b16 v173, v77 offset:28368
	v_add_f32_e32 v77, v192, v47
	v_mul_f32_e32 v77, 0x3fb8aa3b, v77
	v_exp_f32_e32 v77, v77
	v_pk_mul_f32 v[40:41], v[46:47], v[40:41] op_sel_hi:[0,1]
	v_pk_mul_f32 v[82:83], v[82:83], v[88:89]
	v_pk_mul_f32 v[78:79], v[90:91], v[40:41]
	v_pk_mul_f32 v[88:89], v[186:187], v[40:41]
	v_cvt_pk_bf16_f32 v40, v36, v37
	v_rcp_f32_e32 v36, v77
	ds_write_b16 v173, v87 offset:432
	v_cvt_pk_bf16_f32 v87, v82, v83
	v_cvt_pk_bf16_f32 v82, v37, s0
	v_mul_f32_e32 v37, v100, v36
	v_mul_f32_e32 v41, v42, v36
	v_cvt_pk_bf16_f32 v37, v37, s0
	ds_write_b16 v173, v37 offset:10080
	v_cvt_pk_bf16_f32 v37, v41, s0
	v_add_f32_e32 v41, v52, v47
	v_mul_f32_e32 v41, 0x3fb8aa3b, v41
	v_exp_f32_e32 v41, v41
	v_cvt_pk_bf16_f32 v96, v78, v79
	v_mul_f32_e32 v78, v188, v77
	ds_write_b16 v173, v37 offset:19296
	v_cvt_pk_bf16_f32 v37, v78, s0
	ds_write_b16 v173, v37 offset:28512
	v_rcp_f32_e32 v37, v41
	v_pk_mul_f32 v[44:45], v[76:77], v[44:45] neg_lo:[0,1] neg_hi:[0,1]
	v_mul_f32_e32 v41, v191, v41
	v_cvt_pk_bf16_f32 v47, v44, s0
	ds_write_b16 v173, v47 offset:864
	v_mul_f32_e32 v47, v101, v37
	v_mul_f32_e32 v52, v43, v37
	v_cvt_pk_bf16_f32 v47, v47, s0
	ds_write_b16 v173, v47 offset:10224
	v_cvt_pk_bf16_f32 v47, v52, s0
	v_cvt_pk_bf16_f32 v41, v41, s0
	v_pk_mul_f32 v[36:37], v[46:47], v[36:37] op_sel_hi:[0,1]
	v_cvt_pk_bf16_f32 v76, v45, s0
	ds_write_b16 v173, v41 offset:28656
	v_pk_mul_f32 v[42:43], v[42:43], v[36:37]
	v_pk_mul_f32 v[36:37], v[100:101], v[36:37]
	v_cvt_pk_bf16_f32 v41, v44, v45
	ds_write_b16 v173, v82 offset:720
	v_cvt_pk_bf16_f32 v82, v84, v85
	v_cvt_pk_bf16_f32 v88, v88, v89
	ds_write_b16 v173, v76 offset:1008
	ds_write_b16 v173, v47 offset:19440
	v_cvt_pk_bf16_f32 v97, v42, v43
	v_cvt_pk_bf16_f32 v89, v36, v37
	v_cvt_pk_bf16_f32 v83, v92, v93
	ds_write_b128 v141, v[38:41] offset:36864
	ds_write_b128 v141, v[80:83] offset:46080
	ds_write_b128 v141, v[86:89] offset:55296
	ds_write_b128 v141, v[94:97] offset:64512
	s_waitcnt lgkmcnt(0)
	s_barrier
	v_add_u32_e32 v76, v106, v110
	ds_read_b128 v[36:39], v76
	ds_read_b128 v[40:43], v76 offset:64
	ds_read_b128 v[44:47], v107 offset:9216
	ds_read_b128 v[78:81], v107 offset:9280
	s_waitcnt lgkmcnt(1)
	v_mfma_f32_16x16x32_bf16 v[36:39], v[36:39], v[44:47], 0
	ds_read_b128 v[44:47], v76 offset:18432
	v_mov_b32_e32 v52, s95
	s_waitcnt lgkmcnt(1)
	v_mfma_f32_16x16x32_bf16 v[36:39], v[40:43], v[78:81], v[36:39]
	ds_read_b128 v[40:43], v76 offset:18496
	ds_read_b128 v[78:81], v107
	ds_read_b128 v[82:85], v107 offset:64
	s_waitcnt lgkmcnt(1)
	v_mfma_f32_16x16x32_bf16 v[78:81], v[44:47], v[78:81], 0
	s_nop 2
	v_cndmask_b32_e64 v77, v52, v36, s[48:49]
	v_mov_b32_e32 v36, s95
	v_cndmask_b32_e64 v37, v37, 0, s[50:51]
	s_waitcnt lgkmcnt(0)
	v_mfma_f32_16x16x32_bf16 v[78:81], v[40:43], v[82:85], v[78:81]
	ds_read_b128 v[82:85], v107 offset:27648
	ds_read_b128 v[86:89], v107 offset:27712
	ds_read_b128 v[90:93], v76 offset:9216
	v_cndmask_b32_e64 v38, 0, v38, s[52:53]
	s_waitcnt lgkmcnt(2)
	v_mfma_f32_16x16x32_bf16 v[44:47], v[44:47], v[82:85], 0
	v_cndmask_b32_e64 v39, 0, v39, s[54:55]
	s_nop 0
	v_cndmask_b32_e64 v80, 0, v80, s[38:39]
	v_cndmask_b32_e64 v79, 0, v79, s[40:41]
	s_waitcnt lgkmcnt(1)
	v_mfma_f32_16x16x32_bf16 v[40:43], v[40:43], v[86:89], v[44:47]
	v_cndmask_b32_e32 v78, 0, v78, vcc
	s_or_b64 vcc, s[46:47], s[58:59]
	s_nop 0
	ds_read_b128 v[44:47], v76 offset:9280
	s_waitcnt lgkmcnt(1)
	v_mfma_f32_16x16x32_bf16 v[82:85], v[90:93], v[82:85], 0
	s_nop 1
	v_cndmask_b32_e64 v36, v40, v36, s[48:49]
	v_cndmask_b32_e64 v40, v36, v40, s[50:51]
	v_cvt_pk_bf16_f32 v36, v77, v37
	s_waitcnt lgkmcnt(0)
	v_mfma_f32_16x16x32_bf16 v[44:47], v[44:47], v[86:89], v[82:85]
	v_cvt_pk_bf16_f32 v37, v38, v39
	v_add_u32_e32 v38, s33, v127
	v_cndmask_b32_e64 v41, 0, v41, s[50:51]
	s_nop 4
	v_cndmask_b32_e64 v52, v44, v52, s[48:49]
	v_cndmask_b32_e64 v44, v52, v44, s[50:51]
	v_cndmask_b32_e64 v52, 0, v81, s[36:37]
	v_cndmask_b32_e64 v42, v42, 0, s[52:53]
	v_cndmask_b32_e64 v43, v43, 0, s[54:55]
	ds_write_b64 v38, v[36:37]
	ds_write_b16 v148, v36
	ds_write_b16_d16_hi v148, v36 offset:144
	ds_write_b16 v148, v37 offset:288
	ds_write_b16_d16_hi v148, v37 offset:432
	v_cvt_pk_bf16_f32 v36, v78, v79
	v_cvt_pk_bf16_f32 v37, v80, v52
	v_add_u32_e32 v38, s2, v127
	v_cndmask_b32_e64 v45, 0, v45, s[50:51]
	v_cndmask_b32_e64 v46, v46, 0, s[52:53]
	v_cndmask_b32_e64 v47, v47, 0, s[54:55]
	ds_write_b64 v38, v[36:37]
	v_cvt_pk_bf16_f32 v36, v40, v41
	v_cvt_pk_bf16_f32 v37, v42, v43
	v_add_u32_e32 v38, s0, v127
	ds_write_b64 v38, v[36:37]
	v_cvt_pk_bf16_f32 v36, v44, v45
	v_cvt_pk_bf16_f32 v37, v46, v47
	v_add_u32_e32 v38, s3, v127
	ds_write_b64 v38, v[36:37]
	v_add_u32_e32 v36, s74, v127
	ds_write_b64 v36, v[60:61]
	v_add_u32_e32 v77, v106, v128
	ds_read_b128 v[36:39], v77
	ds_read_b128 v[40:43], v77 offset:64
	ds_read_b128 v[44:47], v107 offset:9216
	ds_read_b128 v[78:81], v107 offset:9280
	s_waitcnt lgkmcnt(1)
	v_mfma_f32_16x16x32_bf16 v[36:39], v[36:39], v[44:47], 0
	ds_read_b128 v[44:47], v77 offset:18432
	v_mov_b32_e32 v52, s95
	s_waitcnt lgkmcnt(1)
	v_mfma_f32_16x16x32_bf16 v[36:39], v[40:43], v[78:81], v[36:39]
	ds_read_b128 v[40:43], v77 offset:18496
	ds_read_b128 v[78:81], v107
	ds_read_b128 v[82:85], v107 offset:64
	s_waitcnt lgkmcnt(1)
	v_mfma_f32_16x16x32_bf16 v[78:81], v[44:47], v[78:81], 0
	s_nop 2
	v_cndmask_b32_e64 v37, v37, 0, s[58:59]
	v_cndmask_b32_e64 v38, 0, v38, s[60:61]
	v_cndmask_b32_e64 v39, 0, v39, s[62:63]
	s_waitcnt lgkmcnt(0)
	v_mfma_f32_16x16x32_bf16 v[78:81], v[40:43], v[82:85], v[78:81]
	ds_read_b128 v[82:85], v107 offset:27648
	ds_read_b128 v[86:89], v107 offset:27712
	ds_read_b128 v[90:93], v77 offset:9216
	s_waitcnt lgkmcnt(2)
; __device__ __forceinline__ void st4_lds(LAS unsigned char* p, f32x4 v) { v2u w; w.x = pk2(v[0], v[1]); w.y = pk2(v[2], v[3]); *(LAS v2u*)p = w; }
; __device__ __forceinline__ f32x4 ld4_lds(const LAS unsigned char* p) { const v2u w = *(const LAS v2u*)p; return (f32x4){bflo(w.x), bfhi(w.x), bflo(w.y), bfhi(w.y)}; }
; #define LBAR() asm volatile("s_waitcnt lgkmcnt(0)\n\ts_barrier" ::: "memory")
; __device__ __forceinline__ void rwkv_chunk_group(Frame& F, int bc, unsigned long long& tsub) {
;     ...
;         for (int v = 0; v < 4; ++v) { const int qq = q0 + 4 * fq + v;
;             if (!(p < qq)) m[v] = 0.f;
;             if (!(qq < p)) nak[v] = 0.f;
;             if (!(qq <= p)) { nrk[v] = 0.f; nrb[v] = 0.f; }
;             tt[v] = (p == qq) ? 1.f : 0.f; }
;         const int o = p * LD + (q0 + 4 * fq) * 2;
;         st4_lds(L + L_M + o, m); st4t_lds(L + L_MT, p, q0 + 4 * fq, m); st4_lds(L + L_NAK + o, nak); st4_lds(L + L_NRK + o, nrk); st4_lds(L + L_NRB + o, nrb); st4_lds(L + L_TT + o, tt);
;     ...
;     for (int it = 0; it < 6; ++it) {
;         const int rM = (it & 1) ? L_AT : L_M, rMT = (it & 1) ? L_BT : L_MT, rTT = (it & 1) ? L_KT : L_TT;
;         const int wM = (it & 1) ? L_M : L_AT, wMT = (it & 1) ? L_MT : L_BT, wTT = (it & 1) ? L_TT : L_KT;
; #pragma unroll
;         for (int q = 0; q < 2; ++q) { const int tw = 2 * w + q, p0 = 16 * (tw >> 2), q0 = 16 * (tw & 3); const int o = (p0 + fr) * LD + (q0 + 4 * fq) * 2;
;             f32x4 tn = Z4, mn = Z4;
;             if (q0 <= p0) { tn = mm_tile(L + rM, LD, q0, L + rTT, LD, p0, 2, ld4_lds(L + rTT + o), fr, fq);
;                           }
;             if (q0 >= p0 && it < 5) mn = mm_tile(L + rMT, LD, q0, L + rM, LD, p0, 2, Z4, fr, fq);
;             st4_lds(L + wTT + o, tn); if (it < 5) { st4_lds(L + wM + o, mn); st4t_lds(L + wMT, p0 + fr, q0 + 4 * fq, mn); } }
;         LBAR();
;     }
	v_mfma_f32_16x16x32_bf16 v[44:47], v[44:47], v[82:85], 0
	s_nop 2
	v_cndmask_b32_e64 v80, 0, v80, s[44:45]
	v_cndmask_b32_e64 v79, 0, v79, s[46:47]
	v_cndmask_b32_e32 v78, 0, v78, vcc
	s_waitcnt lgkmcnt(1)
	v_mfma_f32_16x16x32_bf16 v[40:43], v[40:43], v[86:89], v[44:47]
	s_andn2_b64 vcc, exec, s[78:79]
	s_nop 1
	ds_read_b128 v[44:47], v77 offset:9280
	s_waitcnt lgkmcnt(1)
	v_mfma_f32_16x16x32_bf16 v[82:85], v[90:93], v[82:85], 0
	s_nop 1
	v_cndmask_b32_e64 v41, 0, v41, s[58:59]
	v_cndmask_b32_e64 v42, v42, 0, s[60:61]
	v_cndmask_b32_e64 v43, v43, 0, s[62:63]
	s_waitcnt lgkmcnt(0)
	v_mfma_f32_16x16x32_bf16 v[44:47], v[44:47], v[86:89], v[82:85]
	s_nop 2
	v_cndmask_b32_e64 v82, v52, v36, s[56:57]
	v_mov_b32_e32 v36, s95
	v_cndmask_b32_e64 v36, v40, v36, s[56:57]
	s_nop 1
	v_cndmask_b32_e64 v52, v44, v52, s[56:57]
	v_cndmask_b32_e64 v44, v52, v44, s[58:59]
	v_cndmask_b32_e64 v40, v36, v40, s[58:59]
	v_cndmask_b32_e64 v52, 0, v81, s[42:43]
	v_cvt_pk_bf16_f32 v36, v82, v37
	v_cvt_pk_bf16_f32 v37, v38, v39
	v_add_u32_e32 v38, s33, v129
	ds_write_b64 v38, v[36:37]
	ds_write_b16 v149, v36
	ds_write_b16_d16_hi v149, v36 offset:144
	ds_write_b16 v149, v37 offset:288
	ds_write_b16_d16_hi v149, v37 offset:432
	v_cvt_pk_bf16_f32 v36, v78, v79
	v_cvt_pk_bf16_f32 v37, v80, v52
	v_add_u32_e32 v38, s2, v129
	v_cndmask_b32_e64 v45, 0, v45, s[58:59]
	v_cndmask_b32_e64 v46, v46, 0, s[60:61]
	v_cndmask_b32_e64 v47, v47, 0, s[62:63]
	ds_write_b64 v38, v[36:37]
	v_cvt_pk_bf16_f32 v36, v40, v41
	v_cvt_pk_bf16_f32 v37, v42, v43
	v_add_u32_e32 v38, s0, v129
	ds_write_b64 v38, v[36:37]
	v_cvt_pk_bf16_f32 v36, v44, v45
	v_cvt_pk_bf16_f32 v37, v46, v47
	v_add_u32_e32 v38, s3, v129
	ds_write_b64 v38, v[36:37]
	v_add_u32_e32 v36, s74, v129
	ds_write_b64 v36, v[72:73]
	s_waitcnt lgkmcnt(0)
	s_barrier
	v_mov_b32_e32 v78, v127
	v_mov_b32_e32 v79, v129
	v_add_u32_e32 v173, v106, v110
	v_add_u32_e32 v174, v106, v128
	v_add_u32_e32 v97, 0x12000, v127
	v_add_u32_e32 v98, 0x12000, v129
	v_mov_b32_e32 v102, 0
	v_mov_b32_e32 v103, 0
	v_add_u32_e32 v175, 0x12000, v173
	v_add_u32_e32 v96, 0x12000, v174
	s_and_b64 vcc, exec, s[78:79]
	s_cbranch_vccz .La2_FTFT
	s_and_b64 vcc, exec, s[84:85]
	s_cbranch_vccz .La2_TFTx
	ds_read_b64 v[228:229], v97 offset:18432
	ds_read_b128 v[176:179], v175 offset:0
	ds_read_b128 v[212:215], v132 offset:18432
	ds_read_b128 v[184:187], v175 offset:9216
	ds_read_b128 v[220:223], v132 offset:0
	ds_read_b128 v[200:203], v96 offset:9216
	ds_read_b128 v[180:183], v175 offset:64
	ds_read_b128 v[216:219], v132 offset:18496
	ds_read_b128 v[188:191], v175 offset:9280
	ds_read_b128 v[224:227], v132 offset:64
	ds_read_b128 v[204:207], v96 offset:9280
	s_waitcnt lgkmcnt(10)
	v_lshlrev_b32_e32 v232, 16, v228
	v_and_b32_e32 v233, 0xffff0000, v228
	v_lshlrev_b32_e32 v234, 16, v229
	v_and_b32_e32 v235, 0xffff0000, v229
	s_nop 1
	s_waitcnt lgkmcnt(8)
	v_mfma_f32_16x16x32_bf16 v[232:235], v[176:179], v[212:215], v[232:235]
	s_waitcnt lgkmcnt(6)
	v_mfma_f32_16x16x32_bf16 v[236:239], v[184:187], v[220:223], 0
	s_waitcnt lgkmcnt(5)
	v_mfma_f32_16x16x32_bf16 v[244:247], v[200:203], v[220:223], 0
	s_waitcnt lgkmcnt(3)
	v_mfma_f32_16x16x32_bf16 v[232:235], v[180:183], v[216:219], v[232:235]
	s_waitcnt lgkmcnt(1)
	v_mfma_f32_16x16x32_bf16 v[236:239], v[188:191], v[224:227], v[236:239]
	s_waitcnt lgkmcnt(0)
	v_mfma_f32_16x16x32_bf16 v[244:247], v[204:207], v[224:227], v[244:247]
	s_nop 7
	v_cvt_pk_bf16_f32 v248, v232, v233
	v_cvt_pk_bf16_f32 v249, v234, v235
	v_cvt_pk_bf16_f32 v250, v236, v237
	v_cvt_pk_bf16_f32 v251, v238, v239
	v_cvt_pk_bf16_f32 v100, v244, v245
	v_cvt_pk_bf16_f32 v101, v246, v247
	ds_write_b64 v127, v[248:249] offset:18432
	ds_write_b64 v127, v[250:251] offset:0
	ds_write_b16 v151, v250 offset:9216
	ds_write_b16_d16_hi v151, v250 offset:9360
	ds_write_b16 v151, v251 offset:9504
	ds_write_b16_d16_hi v151, v251 offset:9648
	ds_write_b64 v129, v[102:103] offset:18432
	ds_write_b64 v129, v[100:101] offset:0
	ds_write_b16 v152, v100 offset:9216
	ds_write_b16_d16_hi v152, v100 offset:9360
	ds_write_b16 v152, v101 offset:9504
	ds_write_b16_d16_hi v152, v101 offset:9648
	s_waitcnt lgkmcnt(0)
	s_barrier
	ds_read_b64 v[228:229], v127 offset:18432
	ds_read_b128 v[176:179], v173 offset:0
	ds_read_b128 v[212:215], v107 offset:18432
	ds_read_b128 v[184:187], v173 offset:9216
	ds_read_b128 v[220:223], v107 offset:0
	ds_read_b128 v[200:203], v174 offset:9216
	ds_read_b128 v[180:183], v173 offset:64
	ds_read_b128 v[216:219], v107 offset:18496
	ds_read_b128 v[188:191], v173 offset:9280
	ds_read_b128 v[224:227], v107 offset:64
	ds_read_b128 v[204:207], v174 offset:9280
	s_waitcnt lgkmcnt(10)
	v_lshlrev_b32_e32 v232, 16, v228
	v_and_b32_e32 v233, 0xffff0000, v228
	v_lshlrev_b32_e32 v234, 16, v229
	v_and_b32_e32 v235, 0xffff0000, v229
	s_nop 1
	s_waitcnt lgkmcnt(8)
	v_mfma_f32_16x16x32_bf16 v[232:235], v[176:179], v[212:215], v[232:235]
	s_waitcnt lgkmcnt(6)
	v_mfma_f32_16x16x32_bf16 v[236:239], v[184:187], v[220:223], 0
	s_waitcnt lgkmcnt(5)
	v_mfma_f32_16x16x32_bf16 v[244:247], v[200:203], v[220:223], 0
	s_waitcnt lgkmcnt(3)
	v_mfma_f32_16x16x32_bf16 v[232:235], v[180:183], v[216:219], v[232:235]
	s_waitcnt lgkmcnt(1)
	v_mfma_f32_16x16x32_bf16 v[236:239], v[188:191], v[224:227], v[236:239]
	s_waitcnt lgkmcnt(0)
	v_mfma_f32_16x16x32_bf16 v[244:247], v[204:207], v[224:227], v[244:247]
	s_nop 7
	v_cvt_pk_bf16_f32 v248, v232, v233
	v_cvt_pk_bf16_f32 v249, v234, v235
	v_cvt_pk_bf16_f32 v250, v236, v237
	v_cvt_pk_bf16_f32 v251, v238, v239
	v_cvt_pk_bf16_f32 v100, v244, v245
	v_cvt_pk_bf16_f32 v101, v246, v247
	ds_write_b64 v97, v[248:249] offset:18432
	ds_write_b64 v97, v[250:251] offset:0
	ds_write_b16 v148, v250 offset:0
	ds_write_b16_d16_hi v148, v250 offset:144
	ds_write_b16 v148, v251 offset:288
	ds_write_b16_d16_hi v148, v251 offset:432
	ds_write_b64 v98, v[102:103] offset:18432
	ds_write_b64 v98, v[100:101] offset:0
	ds_write_b16 v149, v100 offset:0
	ds_write_b16_d16_hi v149, v100 offset:144
	ds_write_b16 v149, v101 offset:288
	ds_write_b16_d16_hi v149, v101 offset:432
	s_waitcnt lgkmcnt(0)
	s_barrier
; __device__ __forceinline__ void st4_lds(LAS unsigned char* p, f32x4 v) { v2u w; w.x = pk2(v[0], v[1]); w.y = pk2(v[2], v[3]); *(LAS v2u*)p = w; }
; __device__ __forceinline__ f32x4 ld4_lds(const LAS unsigned char* p) { const v2u w = *(const LAS v2u*)p; return (f32x4){bflo(w.x), bfhi(w.x), bflo(w.y), bfhi(w.y)}; }
; #define LBAR() asm volatile("s_waitcnt lgkmcnt(0)\n\ts_barrier" ::: "memory")
; __device__ __forceinline__ void rwkv_chunk_group(Frame& F, int bc, unsigned long long& tsub) {
;     ...
;     for (int it = 0; it < 6; ++it) {
;         const int rM = (it & 1) ? L_AT : L_M, rMT = (it & 1) ? L_BT : L_MT, rTT = (it & 1) ? L_KT : L_TT;
;         const int wM = (it & 1) ? L_M : L_AT, wMT = (it & 1) ? L_MT : L_BT, wTT = (it & 1) ? L_TT : L_KT;
; #pragma unroll
;         for (int q = 0; q < 2; ++q) { const int tw = 2 * w + q, p0 = 16 * (tw >> 2), q0 = 16 * (tw & 3); const int o = (p0 + fr) * LD + (q0 + 4 * fq) * 2;
;             f32x4 tn = Z4, mn = Z4;
;             if (q0 <= p0) { tn = mm_tile(L + rM, LD, q0, L + rTT, LD, p0, 2, ld4_lds(L + rTT + o), fr, fq);
;                           }
;             if (q0 >= p0 && it < 5) mn = mm_tile(L + rMT, LD, q0, L + rM, LD, p0, 2, Z4, fr, fq);
;             st4_lds(L + wTT + o, tn); if (it < 5) { st4_lds(L + wM + o, mn); st4t_lds(L + wMT, p0 + fr, q0 + 4 * fq, mn); } }
;         LBAR();
;     }
	ds_read_b64 v[228:229], v97 offset:18432
	ds_read_b128 v[176:179], v175 offset:0
	ds_read_b128 v[212:215], v132 offset:18432
	ds_read_b128 v[184:187], v175 offset:9216
	ds_read_b128 v[220:223], v132 offset:0
	ds_read_b128 v[200:203], v96 offset:9216
	ds_read_b128 v[180:183], v175 offset:64
	ds_read_b128 v[216:219], v132 offset:18496
	ds_read_b128 v[188:191], v175 offset:9280
	ds_read_b128 v[224:227], v132 offset:64
	ds_read_b128 v[204:207], v96 offset:9280
	s_waitcnt lgkmcnt(10)
	v_lshlrev_b32_e32 v232, 16, v228
	v_and_b32_e32 v233, 0xffff0000, v228
	v_lshlrev_b32_e32 v234, 16, v229
	v_and_b32_e32 v235, 0xffff0000, v229
	s_nop 1
	s_waitcnt lgkmcnt(8)
	v_mfma_f32_16x16x32_bf16 v[232:235], v[176:179], v[212:215], v[232:235]
	s_waitcnt lgkmcnt(6)
	v_mfma_f32_16x16x32_bf16 v[236:239], v[184:187], v[220:223], 0
	s_waitcnt lgkmcnt(5)
	v_mfma_f32_16x16x32_bf16 v[244:247], v[200:203], v[220:223], 0
	s_waitcnt lgkmcnt(3)
	v_mfma_f32_16x16x32_bf16 v[232:235], v[180:183], v[216:219], v[232:235]
	s_waitcnt lgkmcnt(1)
	v_mfma_f32_16x16x32_bf16 v[236:239], v[188:191], v[224:227], v[236:239]
	s_waitcnt lgkmcnt(0)
	v_mfma_f32_16x16x32_bf16 v[244:247], v[204:207], v[224:227], v[244:247]
	s_nop 7
	v_cvt_pk_bf16_f32 v248, v232, v233
	v_cvt_pk_bf16_f32 v249, v234, v235
	v_cvt_pk_bf16_f32 v250, v236, v237
	v_cvt_pk_bf16_f32 v251, v238, v239
	v_cvt_pk_bf16_f32 v100, v244, v245
	v_cvt_pk_bf16_f32 v101, v246, v247
	ds_write_b64 v127, v[248:249] offset:18432
	ds_write_b64 v127, v[250:251] offset:0
	ds_write_b16 v151, v250 offset:9216
	ds_write_b16_d16_hi v151, v250 offset:9360
	ds_write_b16 v151, v251 offset:9504
	ds_write_b16_d16_hi v151, v251 offset:9648
	ds_write_b64 v129, v[102:103] offset:18432
	ds_write_b64 v129, v[100:101] offset:0
	ds_write_b16 v152, v100 offset:9216
	ds_write_b16_d16_hi v152, v100 offset:9360
	ds_write_b16 v152, v101 offset:9504
	ds_write_b16_d16_hi v152, v101 offset:9648
	s_waitcnt lgkmcnt(0)
	s_barrier
	ds_read_b64 v[228:229], v127 offset:18432
	ds_read_b128 v[176:179], v173 offset:0
	ds_read_b128 v[212:215], v107 offset:18432
	ds_read_b128 v[184:187], v173 offset:9216
	ds_read_b128 v[220:223], v107 offset:0
	ds_read_b128 v[200:203], v174 offset:9216
	ds_read_b128 v[180:183], v173 offset:64
	ds_read_b128 v[216:219], v107 offset:18496
	ds_read_b128 v[188:191], v173 offset:9280
	ds_read_b128 v[224:227], v107 offset:64
	ds_read_b128 v[204:207], v174 offset:9280
	s_waitcnt lgkmcnt(10)
	v_lshlrev_b32_e32 v232, 16, v228
	v_and_b32_e32 v233, 0xffff0000, v228
	v_lshlrev_b32_e32 v234, 16, v229
	v_and_b32_e32 v235, 0xffff0000, v229
	s_nop 1
	s_waitcnt lgkmcnt(8)
	v_mfma_f32_16x16x32_bf16 v[232:235], v[176:179], v[212:215], v[232:235]
	s_waitcnt lgkmcnt(6)
	v_mfma_f32_16x16x32_bf16 v[236:239], v[184:187], v[220:223], 0
	s_waitcnt lgkmcnt(5)
	v_mfma_f32_16x16x32_bf16 v[244:247], v[200:203], v[220:223], 0
	s_waitcnt lgkmcnt(3)
	v_mfma_f32_16x16x32_bf16 v[232:235], v[180:183], v[216:219], v[232:235]
	s_waitcnt lgkmcnt(1)
	v_mfma_f32_16x16x32_bf16 v[236:239], v[188:191], v[224:227], v[236:239]
	s_waitcnt lgkmcnt(0)
	v_mfma_f32_16x16x32_bf16 v[244:247], v[204:207], v[224:227], v[244:247]
	s_nop 7
	v_cvt_pk_bf16_f32 v248, v232, v233
	v_cvt_pk_bf16_f32 v249, v234, v235
	v_cvt_pk_bf16_f32 v250, v236, v237
	v_cvt_pk_bf16_f32 v251, v238, v239
	v_cvt_pk_bf16_f32 v100, v244, v245
	v_cvt_pk_bf16_f32 v101, v246, v247
	ds_write_b64 v97, v[248:249] offset:18432
	ds_write_b64 v97, v[250:251] offset:0
	ds_write_b16 v148, v250 offset:0
	ds_write_b16_d16_hi v148, v250 offset:144
	ds_write_b16 v148, v251 offset:288
	ds_write_b16_d16_hi v148, v251 offset:432
	ds_write_b64 v98, v[102:103] offset:18432
	ds_write_b64 v98, v[100:101] offset:0
	ds_write_b16 v149, v100 offset:0
	ds_write_b16_d16_hi v149, v100 offset:144
	ds_write_b16 v149, v101 offset:288
	ds_write_b16_d16_hi v149, v101 offset:432
	s_waitcnt lgkmcnt(0)
	s_barrier
	ds_read_b64 v[228:229], v97 offset:18432
	ds_read_b128 v[176:179], v175 offset:0
	ds_read_b128 v[212:215], v132 offset:18432
	ds_read_b128 v[184:187], v175 offset:9216
	ds_read_b128 v[220:223], v132 offset:0
	ds_read_b128 v[200:203], v96 offset:9216
	ds_read_b128 v[180:183], v175 offset:64
	ds_read_b128 v[216:219], v132 offset:18496
	ds_read_b128 v[188:191], v175 offset:9280
	ds_read_b128 v[224:227], v132 offset:64
	ds_read_b128 v[204:207], v96 offset:9280
	s_waitcnt lgkmcnt(10)
	v_lshlrev_b32_e32 v232, 16, v228
	v_and_b32_e32 v233, 0xffff0000, v228
	v_lshlrev_b32_e32 v234, 16, v229
	v_and_b32_e32 v235, 0xffff0000, v229
	s_nop 1
	s_waitcnt lgkmcnt(8)
	v_mfma_f32_16x16x32_bf16 v[232:235], v[176:179], v[212:215], v[232:235]
	s_waitcnt lgkmcnt(6)
	v_mfma_f32_16x16x32_bf16 v[236:239], v[184:187], v[220:223], 0
	s_waitcnt lgkmcnt(5)
	v_mfma_f32_16x16x32_bf16 v[244:247], v[200:203], v[220:223], 0
	s_waitcnt lgkmcnt(3)
	v_mfma_f32_16x16x32_bf16 v[232:235], v[180:183], v[216:219], v[232:235]
	s_waitcnt lgkmcnt(1)
	v_mfma_f32_16x16x32_bf16 v[236:239], v[188:191], v[224:227], v[236:239]
	s_waitcnt lgkmcnt(0)
	v_mfma_f32_16x16x32_bf16 v[244:247], v[204:207], v[224:227], v[244:247]
	s_nop 7
	v_cvt_pk_bf16_f32 v248, v232, v233
	v_cvt_pk_bf16_f32 v249, v234, v235
	v_cvt_pk_bf16_f32 v250, v236, v237
	v_cvt_pk_bf16_f32 v251, v238, v239
	v_cvt_pk_bf16_f32 v100, v244, v245
	v_cvt_pk_bf16_f32 v101, v246, v247
	ds_write_b64 v127, v[248:249] offset:18432
	ds_write_b64 v127, v[250:251] offset:0
	ds_write_b16 v151, v250 offset:9216
	ds_write_b16_d16_hi v151, v250 offset:9360
	ds_write_b16 v151, v251 offset:9504
	ds_write_b16_d16_hi v151, v251 offset:9648
	ds_write_b64 v129, v[102:103] offset:18432
	ds_write_b64 v129, v[100:101] offset:0
	ds_write_b16 v152, v100 offset:9216
	ds_write_b16_d16_hi v152, v100 offset:9360
	ds_write_b16 v152, v101 offset:9504
	ds_write_b16_d16_hi v152, v101 offset:9648
	s_waitcnt lgkmcnt(0)
	s_barrier
	ds_read_b64 v[228:229], v127 offset:18432
	ds_read_b128 v[176:179], v173 offset:0
	ds_read_b128 v[212:215], v107 offset:18432
	ds_read_b128 v[180:183], v173 offset:64
	ds_read_b128 v[216:219], v107 offset:18496
	s_waitcnt lgkmcnt(4)
	v_lshlrev_b32_e32 v232, 16, v228
	v_and_b32_e32 v233, 0xffff0000, v228
	v_lshlrev_b32_e32 v234, 16, v229
	v_and_b32_e32 v235, 0xffff0000, v229
	s_nop 1
	s_waitcnt lgkmcnt(2)
	v_mfma_f32_16x16x32_bf16 v[232:235], v[176:179], v[212:215], v[232:235]
	s_waitcnt lgkmcnt(0)
	v_mfma_f32_16x16x32_bf16 v[232:235], v[180:183], v[216:219], v[232:235]
	s_nop 7
	v_cvt_pk_bf16_f32 v248, v232, v233
	v_cvt_pk_bf16_f32 v249, v234, v235
	ds_write_b64 v97, v[248:249] offset:18432
	ds_write_b64 v98, v[102:103] offset:18432
	s_waitcnt lgkmcnt(0)
	s_barrier
	s_branch .La2_done
; __device__ __forceinline__ void st4_lds(LAS unsigned char* p, f32x4 v) { v2u w; w.x = pk2(v[0], v[1]); w.y = pk2(v[2], v[3]); *(LAS v2u*)p = w; }
; __device__ __forceinline__ f32x4 ld4_lds(const LAS unsigned char* p) { const v2u w = *(const LAS v2u*)p; return (f32x4){bflo(w.x), bfhi(w.x), bflo(w.y), bfhi(w.y)}; }
; #define LBAR() asm volatile("s_waitcnt lgkmcnt(0)\n\ts_barrier" ::: "memory")
; __device__ __forceinline__ void rwkv_chunk_group(Frame& F, int bc, unsigned long long& tsub) {
;     ...
;     for (int it = 0; it < 6; ++it) {
;         const int rM = (it & 1) ? L_AT : L_M, rMT = (it & 1) ? L_BT : L_MT, rTT = (it & 1) ? L_KT : L_TT;
;         const int wM = (it & 1) ? L_M : L_AT, wMT = (it & 1) ? L_MT : L_BT, wTT = (it & 1) ? L_TT : L_KT;
; #pragma unroll
;         for (int q = 0; q < 2; ++q) { const int tw = 2 * w + q, p0 = 16 * (tw >> 2), q0 = 16 * (tw & 3); const int o = (p0 + fr) * LD + (q0 + 4 * fq) * 2;
;             f32x4 tn = Z4, mn = Z4;
;             if (q0 <= p0) { tn = mm_tile(L + rM, LD, q0, L + rTT, LD, p0, 2, ld4_lds(L + rTT + o), fr, fq);
;                           }
;             if (q0 >= p0 && it < 5) mn = mm_tile(L + rMT, LD, q0, L + rM, LD, p0, 2, Z4, fr, fq);
;             st4_lds(L + wTT + o, tn); if (it < 5) { st4_lds(L + wM + o, mn); st4t_lds(L + wMT, p0 + fr, q0 + 4 * fq, mn); } }
;         LBAR();
;     }
.La2_TFTx:
	s_and_b64 vcc, exec, s[90:91]
	s_cbranch_vccz .La2_TFTF
	ds_read_b64 v[228:229], v97 offset:18432
	ds_read_b64 v[230:231], v98 offset:18432
	ds_read_b128 v[176:179], v175 offset:0
	ds_read_b128 v[212:215], v132 offset:18432
	ds_read_b128 v[220:223], v132 offset:0
	ds_read_b128 v[192:195], v96 offset:0
	ds_read_b128 v[200:203], v96 offset:9216
	ds_read_b128 v[180:183], v175 offset:64
	ds_read_b128 v[216:219], v132 offset:18496
	ds_read_b128 v[224:227], v132 offset:64
	ds_read_b128 v[196:199], v96 offset:64
	ds_read_b128 v[204:207], v96 offset:9280
	s_waitcnt lgkmcnt(11)
	v_lshlrev_b32_e32 v232, 16, v228
	v_and_b32_e32 v233, 0xffff0000, v228
	v_lshlrev_b32_e32 v234, 16, v229
	v_and_b32_e32 v235, 0xffff0000, v229
	s_waitcnt lgkmcnt(10)
	v_lshlrev_b32_e32 v240, 16, v230
	v_and_b32_e32 v241, 0xffff0000, v230
	v_lshlrev_b32_e32 v242, 16, v231
	v_and_b32_e32 v243, 0xffff0000, v231
	s_nop 1
	s_waitcnt lgkmcnt(8)
	v_mfma_f32_16x16x32_bf16 v[232:235], v[176:179], v[212:215], v[232:235]
	s_waitcnt lgkmcnt(6)
	v_mfma_f32_16x16x32_bf16 v[240:243], v[192:195], v[212:215], v[240:243]
	s_waitcnt lgkmcnt(5)
	v_mfma_f32_16x16x32_bf16 v[244:247], v[200:203], v[220:223], 0
	s_waitcnt lgkmcnt(3)
	v_mfma_f32_16x16x32_bf16 v[232:235], v[180:183], v[216:219], v[232:235]
	s_waitcnt lgkmcnt(1)
	v_mfma_f32_16x16x32_bf16 v[240:243], v[196:199], v[216:219], v[240:243]
	s_waitcnt lgkmcnt(0)
	v_mfma_f32_16x16x32_bf16 v[244:247], v[204:207], v[224:227], v[244:247]
	s_nop 7
	v_cvt_pk_bf16_f32 v248, v232, v233
	v_cvt_pk_bf16_f32 v249, v234, v235
	v_cvt_pk_bf16_f32 v252, v240, v241
	v_cvt_pk_bf16_f32 v253, v242, v243
	v_cvt_pk_bf16_f32 v100, v244, v245
	v_cvt_pk_bf16_f32 v101, v246, v247
	ds_write_b64 v127, v[248:249] offset:18432
	ds_write_b64 v127, v[102:103] offset:0
	ds_write_b16 v151, v102 offset:9216
	ds_write_b16_d16_hi v151, v102 offset:9360
	ds_write_b16 v151, v103 offset:9504
	ds_write_b16_d16_hi v151, v103 offset:9648
	ds_write_b64 v129, v[252:253] offset:18432
	ds_write_b64 v129, v[100:101] offset:0
	ds_write_b16 v152, v100 offset:9216
	ds_write_b16_d16_hi v152, v100 offset:9360
	ds_write_b16 v152, v101 offset:9504
	ds_write_b16_d16_hi v152, v101 offset:9648
	s_waitcnt lgkmcnt(0)
	s_barrier
	ds_read_b64 v[228:229], v127 offset:18432
	ds_read_b64 v[230:231], v129 offset:18432
	ds_read_b128 v[176:179], v173 offset:0
	ds_read_b128 v[212:215], v107 offset:18432
	ds_read_b128 v[220:223], v107 offset:0
	ds_read_b128 v[192:195], v174 offset:0
	ds_read_b128 v[200:203], v174 offset:9216
	ds_read_b128 v[180:183], v173 offset:64
	ds_read_b128 v[216:219], v107 offset:18496
	ds_read_b128 v[224:227], v107 offset:64
	ds_read_b128 v[196:199], v174 offset:64
	ds_read_b128 v[204:207], v174 offset:9280
	s_waitcnt lgkmcnt(11)
	v_lshlrev_b32_e32 v232, 16, v228
	v_and_b32_e32 v233, 0xffff0000, v228
	v_lshlrev_b32_e32 v234, 16, v229
	v_and_b32_e32 v235, 0xffff0000, v229
	s_waitcnt lgkmcnt(10)
	v_lshlrev_b32_e32 v240, 16, v230
	v_and_b32_e32 v241, 0xffff0000, v230
	v_lshlrev_b32_e32 v242, 16, v231
	v_and_b32_e32 v243, 0xffff0000, v231
	s_nop 1
	s_waitcnt lgkmcnt(8)
	v_mfma_f32_16x16x32_bf16 v[232:235], v[176:179], v[212:215], v[232:235]
	s_waitcnt lgkmcnt(6)
	v_mfma_f32_16x16x32_bf16 v[240:243], v[192:195], v[212:215], v[240:243]
	s_waitcnt lgkmcnt(5)
	v_mfma_f32_16x16x32_bf16 v[244:247], v[200:203], v[220:223], 0
	s_waitcnt lgkmcnt(3)
	v_mfma_f32_16x16x32_bf16 v[232:235], v[180:183], v[216:219], v[232:235]
	s_waitcnt lgkmcnt(1)
	v_mfma_f32_16x16x32_bf16 v[240:243], v[196:199], v[216:219], v[240:243]
	s_waitcnt lgkmcnt(0)
	v_mfma_f32_16x16x32_bf16 v[244:247], v[204:207], v[224:227], v[244:247]
	s_nop 7
	v_cvt_pk_bf16_f32 v248, v232, v233
	v_cvt_pk_bf16_f32 v249, v234, v235
	v_cvt_pk_bf16_f32 v252, v240, v241
	v_cvt_pk_bf16_f32 v253, v242, v243
	v_cvt_pk_bf16_f32 v100, v244, v245
	v_cvt_pk_bf16_f32 v101, v246, v247
	ds_write_b64 v97, v[248:249] offset:18432
	ds_write_b64 v97, v[102:103] offset:0
	ds_write_b16 v148, v102 offset:0
	ds_write_b16_d16_hi v148, v102 offset:144
	ds_write_b16 v148, v103 offset:288
	ds_write_b16_d16_hi v148, v103 offset:432
	ds_write_b64 v98, v[252:253] offset:18432
	ds_write_b64 v98, v[100:101] offset:0
	ds_write_b16 v149, v100 offset:0
	ds_write_b16_d16_hi v149, v100 offset:144
	ds_write_b16 v149, v101 offset:288
	ds_write_b16_d16_hi v149, v101 offset:432
	s_waitcnt lgkmcnt(0)
	s_barrier
	ds_read_b64 v[228:229], v97 offset:18432
	ds_read_b64 v[230:231], v98 offset:18432
	ds_read_b128 v[176:179], v175 offset:0
	ds_read_b128 v[212:215], v132 offset:18432
	ds_read_b128 v[220:223], v132 offset:0
	ds_read_b128 v[192:195], v96 offset:0
	ds_read_b128 v[200:203], v96 offset:9216
	ds_read_b128 v[180:183], v175 offset:64
	ds_read_b128 v[216:219], v132 offset:18496
	ds_read_b128 v[224:227], v132 offset:64
	ds_read_b128 v[196:199], v96 offset:64
	ds_read_b128 v[204:207], v96 offset:9280
	s_waitcnt lgkmcnt(11)
	v_lshlrev_b32_e32 v232, 16, v228
	v_and_b32_e32 v233, 0xffff0000, v228
	v_lshlrev_b32_e32 v234, 16, v229
	v_and_b32_e32 v235, 0xffff0000, v229
	s_waitcnt lgkmcnt(10)
	v_lshlrev_b32_e32 v240, 16, v230
	v_and_b32_e32 v241, 0xffff0000, v230
	v_lshlrev_b32_e32 v242, 16, v231
	v_and_b32_e32 v243, 0xffff0000, v231
	s_nop 1
	s_waitcnt lgkmcnt(8)
	v_mfma_f32_16x16x32_bf16 v[232:235], v[176:179], v[212:215], v[232:235]
	s_waitcnt lgkmcnt(6)
	v_mfma_f32_16x16x32_bf16 v[240:243], v[192:195], v[212:215], v[240:243]
	s_waitcnt lgkmcnt(5)
	v_mfma_f32_16x16x32_bf16 v[244:247], v[200:203], v[220:223], 0
	s_waitcnt lgkmcnt(3)
	v_mfma_f32_16x16x32_bf16 v[232:235], v[180:183], v[216:219], v[232:235]
	s_waitcnt lgkmcnt(1)
	v_mfma_f32_16x16x32_bf16 v[240:243], v[196:199], v[216:219], v[240:243]
	s_waitcnt lgkmcnt(0)
	v_mfma_f32_16x16x32_bf16 v[244:247], v[204:207], v[224:227], v[244:247]
	s_nop 7
	v_cvt_pk_bf16_f32 v248, v232, v233
	v_cvt_pk_bf16_f32 v249, v234, v235
	v_cvt_pk_bf16_f32 v252, v240, v241
	v_cvt_pk_bf16_f32 v253, v242, v243
	v_cvt_pk_bf16_f32 v100, v244, v245
	v_cvt_pk_bf16_f32 v101, v246, v247
	ds_write_b64 v127, v[248:249] offset:18432
	ds_write_b64 v127, v[102:103] offset:0
	ds_write_b16 v151, v102 offset:9216
	ds_write_b16_d16_hi v151, v102 offset:9360
	ds_write_b16 v151, v103 offset:9504
	ds_write_b16_d16_hi v151, v103 offset:9648
	ds_write_b64 v129, v[252:253] offset:18432
	ds_write_b64 v129, v[100:101] offset:0
	ds_write_b16 v152, v100 offset:9216
	ds_write_b16_d16_hi v152, v100 offset:9360
	ds_write_b16 v152, v101 offset:9504
	ds_write_b16_d16_hi v152, v101 offset:9648
	s_waitcnt lgkmcnt(0)
	s_barrier
; __device__ __forceinline__ void st4_lds(LAS unsigned char* p, f32x4 v) { v2u w; w.x = pk2(v[0], v[1]); w.y = pk2(v[2], v[3]); *(LAS v2u*)p = w; }
; __device__ __forceinline__ f32x4 ld4_lds(const LAS unsigned char* p) { const v2u w = *(const LAS v2u*)p; return (f32x4){bflo(w.x), bfhi(w.x), bflo(w.y), bfhi(w.y)}; }
; #define LBAR() asm volatile("s_waitcnt lgkmcnt(0)\n\ts_barrier" ::: "memory")
; __device__ __forceinline__ void rwkv_chunk_group(Frame& F, int bc, unsigned long long& tsub) {
;     ...
;     for (int it = 0; it < 6; ++it) {
;         const int rM = (it & 1) ? L_AT : L_M, rMT = (it & 1) ? L_BT : L_MT, rTT = (it & 1) ? L_KT : L_TT;
;         const int wM = (it & 1) ? L_M : L_AT, wMT = (it & 1) ? L_MT : L_BT, wTT = (it & 1) ? L_TT : L_KT;
; #pragma unroll
;         for (int q = 0; q < 2; ++q) { const int tw = 2 * w + q, p0 = 16 * (tw >> 2), q0 = 16 * (tw & 3); const int o = (p0 + fr) * LD + (q0 + 4 * fq) * 2;
;             f32x4 tn = Z4, mn = Z4;
;             if (q0 <= p0) { tn = mm_tile(L + rM, LD, q0, L + rTT, LD, p0, 2, ld4_lds(L + rTT + o), fr, fq);
;                           }
;             if (q0 >= p0 && it < 5) mn = mm_tile(L + rMT, LD, q0, L + rM, LD, p0, 2, Z4, fr, fq);
;             st4_lds(L + wTT + o, tn); if (it < 5) { st4_lds(L + wM + o, mn); st4t_lds(L + wMT, p0 + fr, q0 + 4 * fq, mn); } }
;         LBAR();
;     }
	ds_read_b64 v[228:229], v127 offset:18432
	ds_read_b64 v[230:231], v129 offset:18432
	ds_read_b128 v[176:179], v173 offset:0
	ds_read_b128 v[212:215], v107 offset:18432
	ds_read_b128 v[220:223], v107 offset:0
	ds_read_b128 v[192:195], v174 offset:0
	ds_read_b128 v[200:203], v174 offset:9216
	ds_read_b128 v[180:183], v173 offset:64
	ds_read_b128 v[216:219], v107 offset:18496
	ds_read_b128 v[224:227], v107 offset:64
	ds_read_b128 v[196:199], v174 offset:64
	ds_read_b128 v[204:207], v174 offset:9280
	s_waitcnt lgkmcnt(11)
	v_lshlrev_b32_e32 v232, 16, v228
	v_and_b32_e32 v233, 0xffff0000, v228
	v_lshlrev_b32_e32 v234, 16, v229
	v_and_b32_e32 v235, 0xffff0000, v229
	s_waitcnt lgkmcnt(10)
	v_lshlrev_b32_e32 v240, 16, v230
	v_and_b32_e32 v241, 0xffff0000, v230
	v_lshlrev_b32_e32 v242, 16, v231
	v_and_b32_e32 v243, 0xffff0000, v231
	s_nop 1
	s_waitcnt lgkmcnt(8)
	v_mfma_f32_16x16x32_bf16 v[232:235], v[176:179], v[212:215], v[232:235]
	s_waitcnt lgkmcnt(6)
	v_mfma_f32_16x16x32_bf16 v[240:243], v[192:195], v[212:215], v[240:243]
	s_waitcnt lgkmcnt(5)
	v_mfma_f32_16x16x32_bf16 v[244:247], v[200:203], v[220:223], 0
	s_waitcnt lgkmcnt(3)
	v_mfma_f32_16x16x32_bf16 v[232:235], v[180:183], v[216:219], v[232:235]
	s_waitcnt lgkmcnt(1)
	v_mfma_f32_16x16x32_bf16 v[240:243], v[196:199], v[216:219], v[240:243]
	s_waitcnt lgkmcnt(0)
	v_mfma_f32_16x16x32_bf16 v[244:247], v[204:207], v[224:227], v[244:247]
	s_nop 7
	v_cvt_pk_bf16_f32 v248, v232, v233
	v_cvt_pk_bf16_f32 v249, v234, v235
	v_cvt_pk_bf16_f32 v252, v240, v241
	v_cvt_pk_bf16_f32 v253, v242, v243
	v_cvt_pk_bf16_f32 v100, v244, v245
	v_cvt_pk_bf16_f32 v101, v246, v247
	ds_write_b64 v97, v[248:249] offset:18432
	ds_write_b64 v97, v[102:103] offset:0
	ds_write_b16 v148, v102 offset:0
	ds_write_b16_d16_hi v148, v102 offset:144
	ds_write_b16 v148, v103 offset:288
	ds_write_b16_d16_hi v148, v103 offset:432
	ds_write_b64 v98, v[252:253] offset:18432
	ds_write_b64 v98, v[100:101] offset:0
	ds_write_b16 v149, v100 offset:0
	ds_write_b16_d16_hi v149, v100 offset:144
	ds_write_b16 v149, v101 offset:288
	ds_write_b16_d16_hi v149, v101 offset:432
	s_waitcnt lgkmcnt(0)
	s_barrier
	ds_read_b64 v[228:229], v97 offset:18432
	ds_read_b64 v[230:231], v98 offset:18432
	ds_read_b128 v[176:179], v175 offset:0
	ds_read_b128 v[212:215], v132 offset:18432
	ds_read_b128 v[220:223], v132 offset:0
	ds_read_b128 v[192:195], v96 offset:0
	ds_read_b128 v[200:203], v96 offset:9216
	ds_read_b128 v[180:183], v175 offset:64
	ds_read_b128 v[216:219], v132 offset:18496
	ds_read_b128 v[224:227], v132 offset:64
	ds_read_b128 v[196:199], v96 offset:64
	ds_read_b128 v[204:207], v96 offset:9280
	s_waitcnt lgkmcnt(11)
	v_lshlrev_b32_e32 v232, 16, v228
	v_and_b32_e32 v233, 0xffff0000, v228
	v_lshlrev_b32_e32 v234, 16, v229
	v_and_b32_e32 v235, 0xffff0000, v229
	s_waitcnt lgkmcnt(10)
	v_lshlrev_b32_e32 v240, 16, v230
	v_and_b32_e32 v241, 0xffff0000, v230
	v_lshlrev_b32_e32 v242, 16, v231
	v_and_b32_e32 v243, 0xffff0000, v231
	s_nop 1
	s_waitcnt lgkmcnt(8)
	v_mfma_f32_16x16x32_bf16 v[232:235], v[176:179], v[212:215], v[232:235]
	s_waitcnt lgkmcnt(6)
	v_mfma_f32_16x16x32_bf16 v[240:243], v[192:195], v[212:215], v[240:243]
	s_waitcnt lgkmcnt(5)
	v_mfma_f32_16x16x32_bf16 v[244:247], v[200:203], v[220:223], 0
	s_waitcnt lgkmcnt(3)
	v_mfma_f32_16x16x32_bf16 v[232:235], v[180:183], v[216:219], v[232:235]
	s_waitcnt lgkmcnt(1)
	v_mfma_f32_16x16x32_bf16 v[240:243], v[196:199], v[216:219], v[240:243]
	s_waitcnt lgkmcnt(0)
	v_mfma_f32_16x16x32_bf16 v[244:247], v[204:207], v[224:227], v[244:247]
	s_nop 7
	v_cvt_pk_bf16_f32 v248, v232, v233
	v_cvt_pk_bf16_f32 v249, v234, v235
	v_cvt_pk_bf16_f32 v252, v240, v241
	v_cvt_pk_bf16_f32 v253, v242, v243
	v_cvt_pk_bf16_f32 v100, v244, v245
	v_cvt_pk_bf16_f32 v101, v246, v247
	ds_write_b64 v127, v[248:249] offset:18432
	ds_write_b64 v127, v[102:103] offset:0
	ds_write_b16 v151, v102 offset:9216
	ds_write_b16_d16_hi v151, v102 offset:9360
	ds_write_b16 v151, v103 offset:9504
	ds_write_b16_d16_hi v151, v103 offset:9648
	ds_write_b64 v129, v[252:253] offset:18432
	ds_write_b64 v129, v[100:101] offset:0
	ds_write_b16 v152, v100 offset:9216
	ds_write_b16_d16_hi v152, v100 offset:9360
	ds_write_b16 v152, v101 offset:9504
	ds_write_b16_d16_hi v152, v101 offset:9648
	s_waitcnt lgkmcnt(0)
	s_barrier
	ds_read_b64 v[228:229], v127 offset:18432
	ds_read_b64 v[230:231], v129 offset:18432
	ds_read_b128 v[176:179], v173 offset:0
	ds_read_b128 v[212:215], v107 offset:18432
	ds_read_b128 v[192:195], v174 offset:0
	ds_read_b128 v[180:183], v173 offset:64
	ds_read_b128 v[216:219], v107 offset:18496
	ds_read_b128 v[196:199], v174 offset:64
	s_waitcnt lgkmcnt(7)
	v_lshlrev_b32_e32 v232, 16, v228
	v_and_b32_e32 v233, 0xffff0000, v228
	v_lshlrev_b32_e32 v234, 16, v229
	v_and_b32_e32 v235, 0xffff0000, v229
	s_waitcnt lgkmcnt(6)
	v_lshlrev_b32_e32 v240, 16, v230
	v_and_b32_e32 v241, 0xffff0000, v230
	v_lshlrev_b32_e32 v242, 16, v231
	v_and_b32_e32 v243, 0xffff0000, v231
	s_nop 1
	s_waitcnt lgkmcnt(4)
	v_mfma_f32_16x16x32_bf16 v[232:235], v[176:179], v[212:215], v[232:235]
	s_waitcnt lgkmcnt(3)
	v_mfma_f32_16x16x32_bf16 v[240:243], v[192:195], v[212:215], v[240:243]
	s_waitcnt lgkmcnt(1)
	v_mfma_f32_16x16x32_bf16 v[232:235], v[180:183], v[216:219], v[232:235]
	s_waitcnt lgkmcnt(0)
	v_mfma_f32_16x16x32_bf16 v[240:243], v[196:199], v[216:219], v[240:243]
	s_nop 7
	v_cvt_pk_bf16_f32 v248, v232, v233
	v_cvt_pk_bf16_f32 v249, v234, v235
	v_cvt_pk_bf16_f32 v252, v240, v241
	v_cvt_pk_bf16_f32 v253, v242, v243
	ds_write_b64 v97, v[248:249] offset:18432
	ds_write_b64 v98, v[252:253] offset:18432
	s_waitcnt lgkmcnt(0)
	s_barrier
	s_branch .La2_done
; __device__ __forceinline__ void st4_lds(LAS unsigned char* p, f32x4 v) { v2u w; w.x = pk2(v[0], v[1]); w.y = pk2(v[2], v[3]); *(LAS v2u*)p = w; }
; __device__ __forceinline__ f32x4 ld4_lds(const LAS unsigned char* p) { const v2u w = *(const LAS v2u*)p; return (f32x4){bflo(w.x), bfhi(w.x), bflo(w.y), bfhi(w.y)}; }
; #define LBAR() asm volatile("s_waitcnt lgkmcnt(0)\n\ts_barrier" ::: "memory")
; __device__ __forceinline__ void rwkv_chunk_group(Frame& F, int bc, unsigned long long& tsub) {
;     ...
;     for (int it = 0; it < 6; ++it) {
;         const int rM = (it & 1) ? L_AT : L_M, rMT = (it & 1) ? L_BT : L_MT, rTT = (it & 1) ? L_KT : L_TT;
;         const int wM = (it & 1) ? L_M : L_AT, wMT = (it & 1) ? L_MT : L_BT, wTT = (it & 1) ? L_TT : L_KT;
; #pragma unroll
;         for (int q = 0; q < 2; ++q) { const int tw = 2 * w + q, p0 = 16 * (tw >> 2), q0 = 16 * (tw & 3); const int o = (p0 + fr) * LD + (q0 + 4 * fq) * 2;
;             f32x4 tn = Z4, mn = Z4;
;             if (q0 <= p0) { tn = mm_tile(L + rM, LD, q0, L + rTT, LD, p0, 2, ld4_lds(L + rTT + o), fr, fq);
;                           }
;             if (q0 >= p0 && it < 5) mn = mm_tile(L + rMT, LD, q0, L + rM, LD, p0, 2, Z4, fr, fq);
;             st4_lds(L + wTT + o, tn); if (it < 5) { st4_lds(L + wM + o, mn); st4t_lds(L + wMT, p0 + fr, q0 + 4 * fq, mn); } }
;         LBAR();
;     }
.La2_TFTF:
	ds_read_b64 v[228:229], v97 offset:18432
	ds_read_b64 v[230:231], v98 offset:18432
	ds_read_b128 v[176:179], v175 offset:0
	ds_read_b128 v[212:215], v132 offset:18432
	ds_read_b128 v[192:195], v96 offset:0
	ds_read_b128 v[180:183], v175 offset:64
	ds_read_b128 v[216:219], v132 offset:18496
	ds_read_b128 v[196:199], v96 offset:64
	s_waitcnt lgkmcnt(7)
	v_lshlrev_b32_e32 v232, 16, v228
	v_and_b32_e32 v233, 0xffff0000, v228
	v_lshlrev_b32_e32 v234, 16, v229
	v_and_b32_e32 v235, 0xffff0000, v229
	s_waitcnt lgkmcnt(6)
	v_lshlrev_b32_e32 v240, 16, v230
	v_and_b32_e32 v241, 0xffff0000, v230
	v_lshlrev_b32_e32 v242, 16, v231
	v_and_b32_e32 v243, 0xffff0000, v231
	s_nop 1
	s_waitcnt lgkmcnt(4)
	v_mfma_f32_16x16x32_bf16 v[232:235], v[176:179], v[212:215], v[232:235]
	s_waitcnt lgkmcnt(3)
	v_mfma_f32_16x16x32_bf16 v[240:243], v[192:195], v[212:215], v[240:243]
	s_waitcnt lgkmcnt(1)
	v_mfma_f32_16x16x32_bf16 v[232:235], v[180:183], v[216:219], v[232:235]
	s_waitcnt lgkmcnt(0)
	v_mfma_f32_16x16x32_bf16 v[240:243], v[196:199], v[216:219], v[240:243]
	s_nop 7
	v_cvt_pk_bf16_f32 v248, v232, v233
	v_cvt_pk_bf16_f32 v249, v234, v235
	v_cvt_pk_bf16_f32 v252, v240, v241
	v_cvt_pk_bf16_f32 v253, v242, v243
	ds_write_b64 v127, v[248:249] offset:18432
	ds_write_b64 v127, v[102:103] offset:0
	ds_write_b16 v151, v102 offset:9216
	ds_write_b16_d16_hi v151, v102 offset:9360
	ds_write_b16 v151, v103 offset:9504
	ds_write_b16_d16_hi v151, v103 offset:9648
	ds_write_b64 v129, v[252:253] offset:18432
	ds_write_b64 v129, v[102:103] offset:0
	ds_write_b16 v152, v102 offset:9216
	ds_write_b16_d16_hi v152, v102 offset:9360
	ds_write_b16 v152, v103 offset:9504
	ds_write_b16_d16_hi v152, v103 offset:9648
	s_waitcnt lgkmcnt(0)
	s_barrier
	ds_read_b64 v[228:229], v127 offset:18432
	ds_read_b64 v[230:231], v129 offset:18432
	ds_read_b128 v[176:179], v173 offset:0
	ds_read_b128 v[212:215], v107 offset:18432
	ds_read_b128 v[192:195], v174 offset:0
	ds_read_b128 v[180:183], v173 offset:64
	ds_read_b128 v[216:219], v107 offset:18496
	ds_read_b128 v[196:199], v174 offset:64
	s_waitcnt lgkmcnt(7)
	v_lshlrev_b32_e32 v232, 16, v228
	v_and_b32_e32 v233, 0xffff0000, v228
	v_lshlrev_b32_e32 v234, 16, v229
	v_and_b32_e32 v235, 0xffff0000, v229
	s_waitcnt lgkmcnt(6)
	v_lshlrev_b32_e32 v240, 16, v230
	v_and_b32_e32 v241, 0xffff0000, v230
	v_lshlrev_b32_e32 v242, 16, v231
	v_and_b32_e32 v243, 0xffff0000, v231
	s_nop 1
	s_waitcnt lgkmcnt(4)
	v_mfma_f32_16x16x32_bf16 v[232:235], v[176:179], v[212:215], v[232:235]
	s_waitcnt lgkmcnt(3)
	v_mfma_f32_16x16x32_bf16 v[240:243], v[192:195], v[212:215], v[240:243]
	s_waitcnt lgkmcnt(1)
	v_mfma_f32_16x16x32_bf16 v[232:235], v[180:183], v[216:219], v[232:235]
	s_waitcnt lgkmcnt(0)
	v_mfma_f32_16x16x32_bf16 v[240:243], v[196:199], v[216:219], v[240:243]
	s_nop 7
	v_cvt_pk_bf16_f32 v248, v232, v233
	v_cvt_pk_bf16_f32 v249, v234, v235
	v_cvt_pk_bf16_f32 v252, v240, v241
	v_cvt_pk_bf16_f32 v253, v242, v243
	ds_write_b64 v97, v[248:249] offset:18432
	ds_write_b64 v97, v[102:103] offset:0
	ds_write_b16 v148, v102 offset:0
	ds_write_b16_d16_hi v148, v102 offset:144
	ds_write_b16 v148, v103 offset:288
	ds_write_b16_d16_hi v148, v103 offset:432
	ds_write_b64 v98, v[252:253] offset:18432
	ds_write_b64 v98, v[102:103] offset:0
	ds_write_b16 v149, v102 offset:0
	ds_write_b16_d16_hi v149, v102 offset:144
	ds_write_b16 v149, v103 offset:288
	ds_write_b16_d16_hi v149, v103 offset:432
	s_waitcnt lgkmcnt(0)
	s_barrier
	ds_read_b64 v[228:229], v97 offset:18432
	ds_read_b64 v[230:231], v98 offset:18432
	ds_read_b128 v[176:179], v175 offset:0
	ds_read_b128 v[212:215], v132 offset:18432
	ds_read_b128 v[192:195], v96 offset:0
	ds_read_b128 v[180:183], v175 offset:64
	ds_read_b128 v[216:219], v132 offset:18496
	ds_read_b128 v[196:199], v96 offset:64
	s_waitcnt lgkmcnt(7)
	v_lshlrev_b32_e32 v232, 16, v228
	v_and_b32_e32 v233, 0xffff0000, v228
	v_lshlrev_b32_e32 v234, 16, v229
	v_and_b32_e32 v235, 0xffff0000, v229
	s_waitcnt lgkmcnt(6)
	v_lshlrev_b32_e32 v240, 16, v230
	v_and_b32_e32 v241, 0xffff0000, v230
	v_lshlrev_b32_e32 v242, 16, v231
	v_and_b32_e32 v243, 0xffff0000, v231
	s_nop 1
	s_waitcnt lgkmcnt(4)
	v_mfma_f32_16x16x32_bf16 v[232:235], v[176:179], v[212:215], v[232:235]
	s_waitcnt lgkmcnt(3)
	v_mfma_f32_16x16x32_bf16 v[240:243], v[192:195], v[212:215], v[240:243]
	s_waitcnt lgkmcnt(1)
	v_mfma_f32_16x16x32_bf16 v[232:235], v[180:183], v[216:219], v[232:235]
	s_waitcnt lgkmcnt(0)
	v_mfma_f32_16x16x32_bf16 v[240:243], v[196:199], v[216:219], v[240:243]
	s_nop 7
	v_cvt_pk_bf16_f32 v248, v232, v233
	v_cvt_pk_bf16_f32 v249, v234, v235
	v_cvt_pk_bf16_f32 v252, v240, v241
	v_cvt_pk_bf16_f32 v253, v242, v243
	ds_write_b64 v127, v[248:249] offset:18432
	ds_write_b64 v127, v[102:103] offset:0
	ds_write_b16 v151, v102 offset:9216
	ds_write_b16_d16_hi v151, v102 offset:9360
	ds_write_b16 v151, v103 offset:9504
	ds_write_b16_d16_hi v151, v103 offset:9648
	ds_write_b64 v129, v[252:253] offset:18432
	ds_write_b64 v129, v[102:103] offset:0
	ds_write_b16 v152, v102 offset:9216
	ds_write_b16_d16_hi v152, v102 offset:9360
	ds_write_b16 v152, v103 offset:9504
	ds_write_b16_d16_hi v152, v103 offset:9648
	s_waitcnt lgkmcnt(0)
	s_barrier
; __device__ __forceinline__ void st4_lds(LAS unsigned char* p, f32x4 v) { v2u w; w.x = pk2(v[0], v[1]); w.y = pk2(v[2], v[3]); *(LAS v2u*)p = w; }
; __device__ __forceinline__ f32x4 ld4_lds(const LAS unsigned char* p) { const v2u w = *(const LAS v2u*)p; return (f32x4){bflo(w.x), bfhi(w.x), bflo(w.y), bfhi(w.y)}; }
; #define LBAR() asm volatile("s_waitcnt lgkmcnt(0)\n\ts_barrier" ::: "memory")
; __device__ __forceinline__ void rwkv_chunk_group(Frame& F, int bc, unsigned long long& tsub) {
;     ...
;     for (int it = 0; it < 6; ++it) {
;         const int rM = (it & 1) ? L_AT : L_M, rMT = (it & 1) ? L_BT : L_MT, rTT = (it & 1) ? L_KT : L_TT;
;         const int wM = (it & 1) ? L_M : L_AT, wMT = (it & 1) ? L_MT : L_BT, wTT = (it & 1) ? L_TT : L_KT;
; #pragma unroll
;         for (int q = 0; q < 2; ++q) { const int tw = 2 * w + q, p0 = 16 * (tw >> 2), q0 = 16 * (tw & 3); const int o = (p0 + fr) * LD + (q0 + 4 * fq) * 2;
;             f32x4 tn = Z4, mn = Z4;
;             if (q0 <= p0) { tn = mm_tile(L + rM, LD, q0, L + rTT, LD, p0, 2, ld4_lds(L + rTT + o), fr, fq);
;                           }
;             if (q0 >= p0 && it < 5) mn = mm_tile(L + rMT, LD, q0, L + rM, LD, p0, 2, Z4, fr, fq);
;             st4_lds(L + wTT + o, tn); if (it < 5) { st4_lds(L + wM + o, mn); st4t_lds(L + wMT, p0 + fr, q0 + 4 * fq, mn); } }
;         LBAR();
;     }
	ds_read_b64 v[228:229], v127 offset:18432
	ds_read_b64 v[230:231], v129 offset:18432
	ds_read_b128 v[176:179], v173 offset:0
	ds_read_b128 v[212:215], v107 offset:18432
	ds_read_b128 v[192:195], v174 offset:0
	ds_read_b128 v[180:183], v173 offset:64
	ds_read_b128 v[216:219], v107 offset:18496
	ds_read_b128 v[196:199], v174 offset:64
	s_waitcnt lgkmcnt(7)
	v_lshlrev_b32_e32 v232, 16, v228
	v_and_b32_e32 v233, 0xffff0000, v228
	v_lshlrev_b32_e32 v234, 16, v229
	v_and_b32_e32 v235, 0xffff0000, v229
	s_waitcnt lgkmcnt(6)
	v_lshlrev_b32_e32 v240, 16, v230
	v_and_b32_e32 v241, 0xffff0000, v230
	v_lshlrev_b32_e32 v242, 16, v231
	v_and_b32_e32 v243, 0xffff0000, v231
	s_nop 1
	s_waitcnt lgkmcnt(4)
	v_mfma_f32_16x16x32_bf16 v[232:235], v[176:179], v[212:215], v[232:235]
	s_waitcnt lgkmcnt(3)
	v_mfma_f32_16x16x32_bf16 v[240:243], v[192:195], v[212:215], v[240:243]
	s_waitcnt lgkmcnt(1)
	v_mfma_f32_16x16x32_bf16 v[232:235], v[180:183], v[216:219], v[232:235]
	s_waitcnt lgkmcnt(0)
	v_mfma_f32_16x16x32_bf16 v[240:243], v[196:199], v[216:219], v[240:243]
	s_nop 7
	v_cvt_pk_bf16_f32 v248, v232, v233
	v_cvt_pk_bf16_f32 v249, v234, v235
	v_cvt_pk_bf16_f32 v252, v240, v241
	v_cvt_pk_bf16_f32 v253, v242, v243
	ds_write_b64 v97, v[248:249] offset:18432
	ds_write_b64 v97, v[102:103] offset:0
	ds_write_b16 v148, v102 offset:0
	ds_write_b16_d16_hi v148, v102 offset:144
	ds_write_b16 v148, v103 offset:288
	ds_write_b16_d16_hi v148, v103 offset:432
	ds_write_b64 v98, v[252:253] offset:18432
	ds_write_b64 v98, v[102:103] offset:0
	ds_write_b16 v149, v102 offset:0
	ds_write_b16_d16_hi v149, v102 offset:144
	ds_write_b16 v149, v103 offset:288
	ds_write_b16_d16_hi v149, v103 offset:432
	s_waitcnt lgkmcnt(0)
	s_barrier
	ds_read_b64 v[228:229], v97 offset:18432
	ds_read_b64 v[230:231], v98 offset:18432
	ds_read_b128 v[176:179], v175 offset:0
	ds_read_b128 v[212:215], v132 offset:18432
	ds_read_b128 v[192:195], v96 offset:0
	ds_read_b128 v[180:183], v175 offset:64
	ds_read_b128 v[216:219], v132 offset:18496
	ds_read_b128 v[196:199], v96 offset:64
	s_waitcnt lgkmcnt(7)
	v_lshlrev_b32_e32 v232, 16, v228
	v_and_b32_e32 v233, 0xffff0000, v228
	v_lshlrev_b32_e32 v234, 16, v229
	v_and_b32_e32 v235, 0xffff0000, v229
	s_waitcnt lgkmcnt(6)
	v_lshlrev_b32_e32 v240, 16, v230
	v_and_b32_e32 v241, 0xffff0000, v230
	v_lshlrev_b32_e32 v242, 16, v231
	v_and_b32_e32 v243, 0xffff0000, v231
	s_nop 1
	s_waitcnt lgkmcnt(4)
	v_mfma_f32_16x16x32_bf16 v[232:235], v[176:179], v[212:215], v[232:235]
	s_waitcnt lgkmcnt(3)
	v_mfma_f32_16x16x32_bf16 v[240:243], v[192:195], v[212:215], v[240:243]
	s_waitcnt lgkmcnt(1)
	v_mfma_f32_16x16x32_bf16 v[232:235], v[180:183], v[216:219], v[232:235]
	s_waitcnt lgkmcnt(0)
	v_mfma_f32_16x16x32_bf16 v[240:243], v[196:199], v[216:219], v[240:243]
	s_nop 7
	v_cvt_pk_bf16_f32 v248, v232, v233
	v_cvt_pk_bf16_f32 v249, v234, v235
	v_cvt_pk_bf16_f32 v252, v240, v241
	v_cvt_pk_bf16_f32 v253, v242, v243
	ds_write_b64 v127, v[248:249] offset:18432
	ds_write_b64 v127, v[102:103] offset:0
	ds_write_b16 v151, v102 offset:9216
	ds_write_b16_d16_hi v151, v102 offset:9360
	ds_write_b16 v151, v103 offset:9504
	ds_write_b16_d16_hi v151, v103 offset:9648
	ds_write_b64 v129, v[252:253] offset:18432
	ds_write_b64 v129, v[102:103] offset:0
	ds_write_b16 v152, v102 offset:9216
	ds_write_b16_d16_hi v152, v102 offset:9360
	ds_write_b16 v152, v103 offset:9504
	ds_write_b16_d16_hi v152, v103 offset:9648
	s_waitcnt lgkmcnt(0)
	s_barrier
	ds_read_b64 v[228:229], v127 offset:18432
	ds_read_b64 v[230:231], v129 offset:18432
	ds_read_b128 v[176:179], v173 offset:0
	ds_read_b128 v[212:215], v107 offset:18432
	ds_read_b128 v[192:195], v174 offset:0
	ds_read_b128 v[180:183], v173 offset:64
	ds_read_b128 v[216:219], v107 offset:18496
	ds_read_b128 v[196:199], v174 offset:64
	s_waitcnt lgkmcnt(7)
	v_lshlrev_b32_e32 v232, 16, v228
	v_and_b32_e32 v233, 0xffff0000, v228
	v_lshlrev_b32_e32 v234, 16, v229
	v_and_b32_e32 v235, 0xffff0000, v229
	s_waitcnt lgkmcnt(6)
	v_lshlrev_b32_e32 v240, 16, v230
	v_and_b32_e32 v241, 0xffff0000, v230
	v_lshlrev_b32_e32 v242, 16, v231
	v_and_b32_e32 v243, 0xffff0000, v231
	s_nop 1
	s_waitcnt lgkmcnt(4)
	v_mfma_f32_16x16x32_bf16 v[232:235], v[176:179], v[212:215], v[232:235]
	s_waitcnt lgkmcnt(3)
	v_mfma_f32_16x16x32_bf16 v[240:243], v[192:195], v[212:215], v[240:243]
	s_waitcnt lgkmcnt(1)
	v_mfma_f32_16x16x32_bf16 v[232:235], v[180:183], v[216:219], v[232:235]
	s_waitcnt lgkmcnt(0)
	v_mfma_f32_16x16x32_bf16 v[240:243], v[196:199], v[216:219], v[240:243]
	s_nop 7
	v_cvt_pk_bf16_f32 v248, v232, v233
	v_cvt_pk_bf16_f32 v249, v234, v235
	v_cvt_pk_bf16_f32 v252, v240, v241
	v_cvt_pk_bf16_f32 v253, v242, v243
	ds_write_b64 v97, v[248:249] offset:18432
	ds_write_b64 v98, v[252:253] offset:18432
	s_waitcnt lgkmcnt(0)
	s_barrier
	s_branch .La2_done
; __device__ __forceinline__ void st4_lds(LAS unsigned char* p, f32x4 v) { v2u w; w.x = pk2(v[0], v[1]); w.y = pk2(v[2], v[3]); *(LAS v2u*)p = w; }
; __device__ __forceinline__ f32x4 ld4_lds(const LAS unsigned char* p) { const v2u w = *(const LAS v2u*)p; return (f32x4){bflo(w.x), bfhi(w.x), bflo(w.y), bfhi(w.y)}; }
; #define LBAR() asm volatile("s_waitcnt lgkmcnt(0)\n\ts_barrier" ::: "memory")
; __device__ __forceinline__ void rwkv_chunk_group(Frame& F, int bc, unsigned long long& tsub) {
;     ...
;     for (int it = 0; it < 6; ++it) {
;         const int rM = (it & 1) ? L_AT : L_M, rMT = (it & 1) ? L_BT : L_MT, rTT = (it & 1) ? L_KT : L_TT;
;         const int wM = (it & 1) ? L_M : L_AT, wMT = (it & 1) ? L_MT : L_BT, wTT = (it & 1) ? L_TT : L_KT;
; #pragma unroll
;         for (int q = 0; q < 2; ++q) { const int tw = 2 * w + q, p0 = 16 * (tw >> 2), q0 = 16 * (tw & 3); const int o = (p0 + fr) * LD + (q0 + 4 * fq) * 2;
;             f32x4 tn = Z4, mn = Z4;
;             if (q0 <= p0) { tn = mm_tile(L + rM, LD, q0, L + rTT, LD, p0, 2, ld4_lds(L + rTT + o), fr, fq);
;                           }
;             if (q0 >= p0 && it < 5) mn = mm_tile(L + rMT, LD, q0, L + rM, LD, p0, 2, Z4, fr, fq);
;             st4_lds(L + wTT + o, tn); if (it < 5) { st4_lds(L + wM + o, mn); st4t_lds(L + wMT, p0 + fr, q0 + 4 * fq, mn); } }
;         LBAR();
;     }
;     if (hh + 1 < RW_H) lora_dma(lora, hnext, lds0, w, lane);
.La2_FTFT:
	ds_read_b128 v[184:187], v175 offset:9216
	ds_read_b128 v[220:223], v132 offset:0
	ds_read_b128 v[200:203], v96 offset:9216
	ds_read_b128 v[188:191], v175 offset:9280
	ds_read_b128 v[224:227], v132 offset:64
	ds_read_b128 v[204:207], v96 offset:9280
	s_waitcnt lgkmcnt(4)
	v_mfma_f32_16x16x32_bf16 v[236:239], v[184:187], v[220:223], 0
	s_waitcnt lgkmcnt(3)
	v_mfma_f32_16x16x32_bf16 v[244:247], v[200:203], v[220:223], 0
	s_waitcnt lgkmcnt(1)
	v_mfma_f32_16x16x32_bf16 v[236:239], v[188:191], v[224:227], v[236:239]
	s_waitcnt lgkmcnt(0)
	v_mfma_f32_16x16x32_bf16 v[244:247], v[204:207], v[224:227], v[244:247]
	s_nop 7
	v_cvt_pk_bf16_f32 v250, v236, v237
	v_cvt_pk_bf16_f32 v251, v238, v239
	v_cvt_pk_bf16_f32 v100, v244, v245
	v_cvt_pk_bf16_f32 v101, v246, v247
	ds_write_b64 v127, v[102:103] offset:18432
	ds_write_b64 v127, v[250:251] offset:0
	ds_write_b16 v151, v250 offset:9216
	ds_write_b16_d16_hi v151, v250 offset:9360
	ds_write_b16 v151, v251 offset:9504
	ds_write_b16_d16_hi v151, v251 offset:9648
	ds_write_b64 v129, v[102:103] offset:18432
	ds_write_b64 v129, v[100:101] offset:0
	ds_write_b16 v152, v100 offset:9216
	ds_write_b16_d16_hi v152, v100 offset:9360
	ds_write_b16 v152, v101 offset:9504
	ds_write_b16_d16_hi v152, v101 offset:9648
	s_waitcnt lgkmcnt(0)
	s_barrier
	ds_read_b128 v[184:187], v173 offset:9216
	ds_read_b128 v[220:223], v107 offset:0
	ds_read_b128 v[200:203], v174 offset:9216
	ds_read_b128 v[188:191], v173 offset:9280
	ds_read_b128 v[224:227], v107 offset:64
	ds_read_b128 v[204:207], v174 offset:9280
	s_waitcnt lgkmcnt(4)
	v_mfma_f32_16x16x32_bf16 v[236:239], v[184:187], v[220:223], 0
	s_waitcnt lgkmcnt(3)
	v_mfma_f32_16x16x32_bf16 v[244:247], v[200:203], v[220:223], 0
	s_waitcnt lgkmcnt(1)
	v_mfma_f32_16x16x32_bf16 v[236:239], v[188:191], v[224:227], v[236:239]
	s_waitcnt lgkmcnt(0)
	v_mfma_f32_16x16x32_bf16 v[244:247], v[204:207], v[224:227], v[244:247]
	s_nop 7
	v_cvt_pk_bf16_f32 v250, v236, v237
	v_cvt_pk_bf16_f32 v251, v238, v239
	v_cvt_pk_bf16_f32 v100, v244, v245
	v_cvt_pk_bf16_f32 v101, v246, v247
	ds_write_b64 v97, v[102:103] offset:18432
	ds_write_b64 v97, v[250:251] offset:0
	ds_write_b16 v148, v250 offset:0
	ds_write_b16_d16_hi v148, v250 offset:144
	ds_write_b16 v148, v251 offset:288
	ds_write_b16_d16_hi v148, v251 offset:432
	ds_write_b64 v98, v[102:103] offset:18432
	ds_write_b64 v98, v[100:101] offset:0
	ds_write_b16 v149, v100 offset:0
	ds_write_b16_d16_hi v149, v100 offset:144
	ds_write_b16 v149, v101 offset:288
	ds_write_b16_d16_hi v149, v101 offset:432
	s_waitcnt lgkmcnt(0)
	s_barrier
	ds_read_b128 v[184:187], v175 offset:9216
	ds_read_b128 v[220:223], v132 offset:0
	ds_read_b128 v[200:203], v96 offset:9216
	ds_read_b128 v[188:191], v175 offset:9280
	ds_read_b128 v[224:227], v132 offset:64
	ds_read_b128 v[204:207], v96 offset:9280
	s_waitcnt lgkmcnt(4)
	v_mfma_f32_16x16x32_bf16 v[236:239], v[184:187], v[220:223], 0
	s_waitcnt lgkmcnt(3)
	v_mfma_f32_16x16x32_bf16 v[244:247], v[200:203], v[220:223], 0
	s_waitcnt lgkmcnt(1)
	v_mfma_f32_16x16x32_bf16 v[236:239], v[188:191], v[224:227], v[236:239]
	s_waitcnt lgkmcnt(0)
	v_mfma_f32_16x16x32_bf16 v[244:247], v[204:207], v[224:227], v[244:247]
	s_nop 7
	v_cvt_pk_bf16_f32 v250, v236, v237
	v_cvt_pk_bf16_f32 v251, v238, v239
	v_cvt_pk_bf16_f32 v100, v244, v245
	v_cvt_pk_bf16_f32 v101, v246, v247
	ds_write_b64 v127, v[102:103] offset:18432
	ds_write_b64 v127, v[250:251] offset:0
	ds_write_b16 v151, v250 offset:9216
	ds_write_b16_d16_hi v151, v250 offset:9360
	ds_write_b16 v151, v251 offset:9504
	ds_write_b16_d16_hi v151, v251 offset:9648
	ds_write_b64 v129, v[102:103] offset:18432
	ds_write_b64 v129, v[100:101] offset:0
	ds_write_b16 v152, v100 offset:9216
	ds_write_b16_d16_hi v152, v100 offset:9360
	ds_write_b16 v152, v101 offset:9504
	ds_write_b16_d16_hi v152, v101 offset:9648
	s_waitcnt lgkmcnt(0)
	s_barrier
	ds_read_b128 v[184:187], v173 offset:9216
	ds_read_b128 v[220:223], v107 offset:0
	ds_read_b128 v[200:203], v174 offset:9216
	ds_read_b128 v[188:191], v173 offset:9280
	ds_read_b128 v[224:227], v107 offset:64
	ds_read_b128 v[204:207], v174 offset:9280
	s_waitcnt lgkmcnt(4)
	v_mfma_f32_16x16x32_bf16 v[236:239], v[184:187], v[220:223], 0
	s_waitcnt lgkmcnt(3)
	v_mfma_f32_16x16x32_bf16 v[244:247], v[200:203], v[220:223], 0
	s_waitcnt lgkmcnt(1)
	v_mfma_f32_16x16x32_bf16 v[236:239], v[188:191], v[224:227], v[236:239]
	s_waitcnt lgkmcnt(0)
	v_mfma_f32_16x16x32_bf16 v[244:247], v[204:207], v[224:227], v[244:247]
	s_nop 7
	v_cvt_pk_bf16_f32 v250, v236, v237
	v_cvt_pk_bf16_f32 v251, v238, v239
	v_cvt_pk_bf16_f32 v100, v244, v245
	v_cvt_pk_bf16_f32 v101, v246, v247
	ds_write_b64 v97, v[102:103] offset:18432
	ds_write_b64 v97, v[250:251] offset:0
	ds_write_b16 v148, v250 offset:0
	ds_write_b16_d16_hi v148, v250 offset:144
	ds_write_b16 v148, v251 offset:288
	ds_write_b16_d16_hi v148, v251 offset:432
	ds_write_b64 v98, v[102:103] offset:18432
	ds_write_b64 v98, v[100:101] offset:0
	ds_write_b16 v149, v100 offset:0
	ds_write_b16_d16_hi v149, v100 offset:144
	ds_write_b16 v149, v101 offset:288
	ds_write_b16_d16_hi v149, v101 offset:432
	s_waitcnt lgkmcnt(0)
	s_barrier
	ds_read_b128 v[184:187], v175 offset:9216
	ds_read_b128 v[220:223], v132 offset:0
	ds_read_b128 v[200:203], v96 offset:9216
	ds_read_b128 v[188:191], v175 offset:9280
	ds_read_b128 v[224:227], v132 offset:64
	ds_read_b128 v[204:207], v96 offset:9280
	s_waitcnt lgkmcnt(4)
	v_mfma_f32_16x16x32_bf16 v[236:239], v[184:187], v[220:223], 0
	s_waitcnt lgkmcnt(3)
	v_mfma_f32_16x16x32_bf16 v[244:247], v[200:203], v[220:223], 0
	s_waitcnt lgkmcnt(1)
	v_mfma_f32_16x16x32_bf16 v[236:239], v[188:191], v[224:227], v[236:239]
	s_waitcnt lgkmcnt(0)
	v_mfma_f32_16x16x32_bf16 v[244:247], v[204:207], v[224:227], v[244:247]
	s_nop 7
	v_cvt_pk_bf16_f32 v250, v236, v237
	v_cvt_pk_bf16_f32 v251, v238, v239
	v_cvt_pk_bf16_f32 v100, v244, v245
	v_cvt_pk_bf16_f32 v101, v246, v247
	ds_write_b64 v127, v[102:103] offset:18432
	ds_write_b64 v127, v[250:251] offset:0
	ds_write_b16 v151, v250 offset:9216
	ds_write_b16_d16_hi v151, v250 offset:9360
	ds_write_b16 v151, v251 offset:9504
	ds_write_b16_d16_hi v151, v251 offset:9648
	ds_write_b64 v129, v[102:103] offset:18432
	ds_write_b64 v129, v[100:101] offset:0
	ds_write_b16 v152, v100 offset:9216
	ds_write_b16_d16_hi v152, v100 offset:9360
	ds_write_b16 v152, v101 offset:9504
	ds_write_b16_d16_hi v152, v101 offset:9648
	s_waitcnt lgkmcnt(0)
	s_barrier
	s_nop 7
	ds_write_b64 v97, v[102:103] offset:18432
	ds_write_b64 v98, v[102:103] offset:18432
	s_waitcnt lgkmcnt(0)
	s_barrier
.La2_done:
	v_readlane_b32 s14, v254, 25
	v_readlane_b32 s15, v254, 26
	s_or_b64 s[14:15], s[14:15], s[96:97]
	s_and_b64 vcc, exec, s[14:15]
	s_cbranch_vccnz .LBB0_1411
	v_readlane_b32 s14, v254, 57
	s_lshl_b32 s13, s13, 6
	v_readlane_b32 s15, v254, 58
	v_add_u32_e32 v40, s13, v51
	v_add_u32_e32 v41, s13, v59
	s_mov_b32 s13, s14
	v_readlane_b32 s14, v254, 23
	s_mov_b32 s15, s17
	s_branch .LBB0_1465
